# v030 + gelu blocks re-emitted + dead zero-inits of conv DPP temps removed in gate-up epilogue + direct per-XCD release in grid barrier
# speedup vs baseline: 1.0063x; 1.0025x over previous
; __device__ __forceinline__ u32x4 pack8(f32x4 v0, f32x4 v1) { u32x4 w; w.x = cvt_pk_bf16(v0[0], v0[1]); w.y = cvt_pk_bf16(v0[2], v0[3]); w.z = cvt_pk_bf16(v1[0], v1[1]); w.w = cvt_pk_bf16(v1[2], v1[3]); return w; }
; __device__ __forceinline__ float dpp_ctl_shl15(float v) { return __int_as_float(__builtin_amdgcn_update_dpp(0, __float_as_int(v), 0x10F, 0xF, 0xF, false)); }
; __device__ __forceinline__ float dpp_ctl_shl14(float v) { return __int_as_float(__builtin_amdgcn_update_dpp(0, __float_as_int(v), 0x10E, 0xF, 0xF, false)); }
;     __device__ __forceinline__ void operator()(const f32x4 (&acc)[2][2][4][2], const Unit& u, int wr, int wc, int fr, int fq) const {
;     ...
;             for (int m = 0; m < 4; ++m) {
;                 f32x4 r[2];
; #pragma unroll
;                 for (int n = 0; n < 2; ++n)
; #pragma unroll
;                     for (int h = 0; h < 2; ++h) {
;                         f32x2 cur, p1, p2;
; #pragma unroll
;                         for (int q = 0; q < 2; ++q) { const int i = 2 * h + q;
;                             const float c_ = acc[ai][0][m][n][i], prev = (m == 0) ? P[n][i] : acc[ai][0][m == 0 ? 0 : m - 1][n][i];
;                             cur[q] = c_; p1[q] = dpp_ctl_shr1(dpp_ctl_shl15(prev), c_); p2[q] = dpp_ctl_shr2(dpp_ctl_shl14(prev), c_); }
;                         const f32x2 kb2 = {kb[n][2 * h], kb[n][2 * h + 1]}, k02 = {k0[n][2 * h], k0[n][2 * h + 1]}, k12 = {k1[n][2 * h], k1[n][2 * h + 1]}, k22 = {k2[n][2 * h], k2[n][2 * h + 1]};
;                         const f32x2 up2 = {acc[ai][1][m][n][2 * h], acc[ai][1][m][n][2 * h + 1]};
;                         const f32x2 cv = kb2 + k02 * p2 + k12 * p1 + k22 * cur;
;                         const f32x2 ex = cv * (-1.4426950408889634f);
;                         f32x2 den; den.x = __builtin_amdgcn_exp2f(ex.x); den.y = __builtin_amdgcn_exp2f(ex.y); den = den + 1.0f;
;                         f32x2 rc; rc.x = __builtin_amdgcn_rcpf(den.x); rc.y = __builtin_amdgcn_rcpf(den.y);
;                         const f32x2 o = (cv * rc) * up2;
;                         r[n][2 * h] = o.x; r[n][2 * h + 1] = o.y;
;                     }
;                 *(u32x4*)(ACT + (size_t)(row0 + ai * HALF + m * 16) * 2816 + f0) = pack8(r[0], r[1]);
.LBB0_844:
	s_or_b64 exec, exec, s[38:39]
	s_waitcnt lgkmcnt(0)
	v_mov_b32_dpp v212, v168 row_shl:14 row_mask:0xf bank_mask:0xf
	v_mov_b32_dpp v213, v169 row_shl:14 row_mask:0xf bank_mask:0xf
	s_nop 0
	v_mov_b32_dpp v212, v150 row_shr:2 row_mask:0xf bank_mask:0xf
	s_nop 0
	v_mov_b32_dpp v213, v151 row_shr:2 row_mask:0xf bank_mask:0xf
	v_mov_b32_dpp v210, v168 row_shl:15 row_mask:0xf bank_mask:0xf
	v_mov_b32_dpp v211, v169 row_shl:15 row_mask:0xf bank_mask:0xf
	s_waitcnt vmcnt(0)
	v_pk_fma_f32 v[168:169], v[90:91], v[212:213], v[106:107]
	v_mov_b32_dpp v214, v170 row_shl:14 row_mask:0xf bank_mask:0xf
	v_mov_b32_dpp v215, v171 row_shl:14 row_mask:0xf bank_mask:0xf
	v_mov_b32_dpp v210, v150 row_shr:1 row_mask:0xf bank_mask:0xf
	v_mov_b32_dpp v211, v151 row_shr:1 row_mask:0xf bank_mask:0xf
	v_mov_b32_dpp v212, v170 row_shl:15 row_mask:0xf bank_mask:0xf
	v_mov_b32_dpp v214, v152 row_shr:2 row_mask:0xf bank_mask:0xf
	v_mov_b32_dpp v213, v171 row_shl:15 row_mask:0xf bank_mask:0xf
	v_mov_b32_dpp v215, v153 row_shr:2 row_mask:0xf bank_mask:0xf
	v_pk_fma_f32 v[168:169], v[94:95], v[210:211], v[168:169]
	v_mov_b32_dpp v212, v152 row_shr:1 row_mask:0xf bank_mask:0xf
	v_mov_b32_dpp v213, v153 row_shr:1 row_mask:0xf bank_mask:0xf
	v_pk_fma_f32 v[170:171], v[92:93], v[214:215], v[108:109]
	v_pk_fma_f32 v[210:211], v[150:151], v[98:99], v[168:169]
	v_pk_fma_f32 v[170:171], v[96:97], v[212:213], v[170:171]
	v_pk_mul_f32 v[168:169], v[210:211], s[60:61] op_sel_hi:[1,0]
	v_pk_fma_f32 v[170:171], v[152:153], v[100:101], v[170:171]
	v_exp_f32_e32 v168, v168
	v_exp_f32_e32 v169, v169
	v_pk_mul_f32 v[212:213], v[170:171], s[60:61] op_sel_hi:[1,0]
	v_mov_b32_e32 v163, 0
	v_exp_f32_e32 v212, v212
	v_exp_f32_e32 v213, v213
	v_pk_add_f32 v[168:169], v[168:169], 1.0 op_sel_hi:[1,0]
	s_nop 0
	v_rcp_f32_e32 v214, v168
	v_rcp_f32_e32 v215, v169
	v_pk_add_f32 v[168:169], v[212:213], 1.0 op_sel_hi:[1,0]
	v_pk_mul_f32 v[210:211], v[210:211], v[214:215]
	v_rcp_f32_e32 v212, v168
	v_rcp_f32_e32 v213, v169
	v_pk_mul_f32 v[158:159], v[158:159], v[210:211]
	v_pk_mul_f32 v[170:171], v[170:171], v[212:213]
	v_mov_b32_dpp v210, v164 row_shl:15 row_mask:0xf bank_mask:0xf
	v_mov_b32_dpp v212, v164 row_shl:14 row_mask:0xf bank_mask:0xf
	v_mov_b32_dpp v213, v165 row_shl:14 row_mask:0xf bank_mask:0xf
	v_mov_b32_dpp v211, v165 row_shl:15 row_mask:0xf bank_mask:0xf
	v_mov_b32_dpp v212, v146 row_shr:2 row_mask:0xf bank_mask:0xf
	v_mov_b32_dpp v213, v147 row_shr:2 row_mask:0xf bank_mask:0xf
	v_mov_b32_dpp v210, v146 row_shr:1 row_mask:0xf bank_mask:0xf
	v_mov_b32_dpp v211, v147 row_shr:1 row_mask:0xf bank_mask:0xf
	v_pk_fma_f32 v[164:165], v[74:75], v[212:213], v[86:87]
	v_mov_b32_dpp v214, v166 row_shl:14 row_mask:0xf bank_mask:0xf
	v_mov_b32_dpp v215, v167 row_shl:14 row_mask:0xf bank_mask:0xf
	v_pk_fma_f32 v[164:165], v[78:79], v[210:211], v[164:165]
	v_mov_b32_dpp v212, v166 row_shl:15 row_mask:0xf bank_mask:0xf
	v_mov_b32_dpp v214, v148 row_shr:2 row_mask:0xf bank_mask:0xf
	v_mov_b32_dpp v213, v167 row_shl:15 row_mask:0xf bank_mask:0xf
	v_mov_b32_dpp v215, v149 row_shr:2 row_mask:0xf bank_mask:0xf
	v_pk_fma_f32 v[164:165], v[146:147], v[82:83], v[164:165]
	v_mov_b32_dpp v212, v148 row_shr:1 row_mask:0xf bank_mask:0xf
	v_mov_b32_dpp v213, v149 row_shr:1 row_mask:0xf bank_mask:0xf
	v_pk_fma_f32 v[166:167], v[76:77], v[214:215], v[88:89]
	v_pk_mul_f32 v[210:211], v[164:165], s[60:61] op_sel_hi:[1,0]
	v_pk_fma_f32 v[166:167], v[80:81], v[212:213], v[166:167]
	v_exp_f32_e32 v210, v210
	v_exp_f32_e32 v211, v211
	v_pk_fma_f32 v[166:167], v[148:149], v[84:85], v[166:167]
	v_pk_mul_f32 v[160:161], v[160:161], v[170:171]
	v_pk_mul_f32 v[212:213], v[166:167], s[60:61] op_sel_hi:[1,0]
	v_pk_add_f32 v[210:211], v[210:211], 1.0 op_sel_hi:[1,0]
	v_exp_f32_e32 v212, v212
	v_exp_f32_e32 v213, v213
	v_rcp_f32_e32 v210, v210
	v_rcp_f32_e32 v211, v211
	v_pk_add_f32 v[212:213], v[212:213], 1.0 op_sel_hi:[1,0]
	v_rcp_f32_e32 v212, v212
	v_rcp_f32_e32 v213, v213
	v_pk_mul_f32 v[164:165], v[164:165], v[210:211]
	v_mov_b32_dpp v170, v150 row_shl:14 row_mask:0xf bank_mask:0xf
	v_pk_mul_f32 v[154:155], v[154:155], v[164:165]
	v_mov_b32_dpp v171, v151 row_shl:14 row_mask:0xf bank_mask:0xf
	v_pk_mul_f32 v[164:165], v[166:167], v[212:213]
	v_cvt_pk_bf16_f32 v158, v158, v159
	v_cvt_pk_bf16_f32 v159, v160, v161
	v_cvt_pk_bf16_f32 v160, v154, v155
	v_lshlrev_b64 v[154:155], 1, v[194:195]
	v_mov_b32_dpp v170, v134 row_shr:2 row_mask:0xf bank_mask:0xf
	v_mov_b32_dpp v171, v135 row_shr:2 row_mask:0xf bank_mask:0xf
	v_mov_b32_dpp v166, v150 row_shl:15 row_mask:0xf bank_mask:0xf
	v_mov_b32_dpp v167, v151 row_shl:15 row_mask:0xf bank_mask:0xf
	v_pk_fma_f32 v[150:151], v[90:91], v[170:171], v[106:107]
	v_mov_b32_dpp v194, v152 row_shl:14 row_mask:0xf bank_mask:0xf
	v_mov_b32_dpp v195, v153 row_shl:14 row_mask:0xf bank_mask:0xf
	v_mov_b32_dpp v166, v134 row_shr:1 row_mask:0xf bank_mask:0xf
	v_mov_b32_dpp v167, v135 row_shr:1 row_mask:0xf bank_mask:0xf
	v_mov_b32_dpp v170, v152 row_shl:15 row_mask:0xf bank_mask:0xf
	v_mov_b32_dpp v194, v136 row_shr:2 row_mask:0xf bank_mask:0xf
	v_mov_b32_dpp v171, v153 row_shl:15 row_mask:0xf bank_mask:0xf
	v_mov_b32_dpp v195, v137 row_shr:2 row_mask:0xf bank_mask:0xf
	v_pk_fma_f32 v[150:151], v[94:95], v[166:167], v[150:151]
	v_mov_b32_dpp v170, v136 row_shr:1 row_mask:0xf bank_mask:0xf
	v_mov_b32_dpp v171, v137 row_shr:1 row_mask:0xf bank_mask:0xf
	v_pk_fma_f32 v[152:153], v[92:93], v[194:195], v[108:109]
	v_pk_fma_f32 v[150:151], v[134:135], v[98:99], v[150:151]
	v_pk_fma_f32 v[152:153], v[96:97], v[170:171], v[152:153]
	v_pk_mul_f32 v[166:167], v[150:151], s[60:61] op_sel_hi:[1,0]
; __device__ __forceinline__ u32x4 pack8(f32x4 v0, f32x4 v1) { u32x4 w; w.x = cvt_pk_bf16(v0[0], v0[1]); w.y = cvt_pk_bf16(v0[2], v0[3]); w.z = cvt_pk_bf16(v1[0], v1[1]); w.w = cvt_pk_bf16(v1[2], v1[3]); return w; }
; __device__ __forceinline__ float dpp_ctl_shl15(float v) { return __int_as_float(__builtin_amdgcn_update_dpp(0, __float_as_int(v), 0x10F, 0xF, 0xF, false)); }
; __device__ __forceinline__ float dpp_ctl_shl14(float v) { return __int_as_float(__builtin_amdgcn_update_dpp(0, __float_as_int(v), 0x10E, 0xF, 0xF, false)); }
;     __device__ __forceinline__ void operator()(const f32x4 (&acc)[2][2][4][2], const Unit& u, int wr, int wc, int fr, int fq) const {
;     ...
;             for (int m = 0; m < 4; ++m) {
;                 f32x4 r[2];
; #pragma unroll
;                 for (int n = 0; n < 2; ++n)
; #pragma unroll
;                     for (int h = 0; h < 2; ++h) {
;                         f32x2 cur, p1, p2;
; #pragma unroll
;                         for (int q = 0; q < 2; ++q) { const int i = 2 * h + q;
;                             const float c_ = acc[ai][0][m][n][i], prev = (m == 0) ? P[n][i] : acc[ai][0][m == 0 ? 0 : m - 1][n][i];
;                             cur[q] = c_; p1[q] = dpp_ctl_shr1(dpp_ctl_shl15(prev), c_); p2[q] = dpp_ctl_shr2(dpp_ctl_shl14(prev), c_); }
;                         const f32x2 kb2 = {kb[n][2 * h], kb[n][2 * h + 1]}, k02 = {k0[n][2 * h], k0[n][2 * h + 1]}, k12 = {k1[n][2 * h], k1[n][2 * h + 1]}, k22 = {k2[n][2 * h], k2[n][2 * h + 1]};
;                         const f32x2 up2 = {acc[ai][1][m][n][2 * h], acc[ai][1][m][n][2 * h + 1]};
;                         const f32x2 cv = kb2 + k02 * p2 + k12 * p1 + k22 * cur;
;                         const f32x2 ex = cv * (-1.4426950408889634f);
;                         f32x2 den; den.x = __builtin_amdgcn_exp2f(ex.x); den.y = __builtin_amdgcn_exp2f(ex.y); den = den + 1.0f;
;                         f32x2 rc; rc.x = __builtin_amdgcn_rcpf(den.x); rc.y = __builtin_amdgcn_rcpf(den.y);
;                         const f32x2 o = (cv * rc) * up2;
;                         r[n][2 * h] = o.x; r[n][2 * h + 1] = o.y;
;                     }
;                 *(u32x4*)(ACT + (size_t)(row0 + ai * HALF + m * 16) * 2816 + f0) = pack8(r[0], r[1]);
	v_pk_fma_f32 v[152:153], v[136:137], v[100:101], v[152:153]
	v_exp_f32_e32 v166, v166
	v_exp_f32_e32 v167, v167
	v_pk_mul_f32 v[170:171], v[152:153], s[60:61] op_sel_hi:[1,0]
	v_pk_mul_f32 v[156:157], v[156:157], v[164:165]
	v_exp_f32_e32 v170, v170
	v_exp_f32_e32 v171, v171
	v_pk_add_f32 v[166:167], v[166:167], 1.0 op_sel_hi:[1,0]
	v_lshl_add_u32 v168, s70, 8, v173
	v_cvt_pk_bf16_f32 v161, v156, v157
	v_mov_b64_e32 v[156:157], s[18:19]
	v_rcp_f32_e32 v166, v166
	v_rcp_f32_e32 v167, v167
	v_pk_add_f32 v[170:171], v[170:171], 1.0 op_sel_hi:[1,0]
	v_mad_i64_i32 v[164:165], s[38:39], v168, s76, v[156:157]
	v_rcp_f32_e32 v170, v170
	v_rcp_f32_e32 v171, v171
	v_lshl_add_u64 v[164:165], v[164:165], 0, v[154:155]
	global_store_dwordx4 v[164:165], v[158:161], off
	v_pk_mul_f32 v[150:151], v[150:151], v[166:167]
	v_mov_b32_e32 v164, 0
	v_pk_mul_f32 v[142:143], v[142:143], v[150:151]
	v_mov_b32_dpp v158, v146 row_shl:14 row_mask:0xf bank_mask:0xf
	v_mov_b32_dpp v159, v147 row_shl:14 row_mask:0xf bank_mask:0xf
	v_pk_mul_f32 v[150:151], v[152:153], v[170:171]
	v_mov_b32_dpp v158, v130 row_shr:2 row_mask:0xf bank_mask:0xf
	v_mov_b32_dpp v159, v131 row_shr:2 row_mask:0xf bank_mask:0xf
	v_mov_b32_dpp v152, v146 row_shl:15 row_mask:0xf bank_mask:0xf
	v_mov_b32_dpp v153, v147 row_shl:15 row_mask:0xf bank_mask:0xf
	v_pk_fma_f32 v[146:147], v[74:75], v[158:159], v[86:87]
	v_mov_b32_dpp v160, v148 row_shl:14 row_mask:0xf bank_mask:0xf
	v_mov_b32_dpp v161, v149 row_shl:14 row_mask:0xf bank_mask:0xf
	v_mov_b32_dpp v152, v130 row_shr:1 row_mask:0xf bank_mask:0xf
	v_mov_b32_dpp v153, v131 row_shr:1 row_mask:0xf bank_mask:0xf
	v_mov_b32_dpp v158, v148 row_shl:15 row_mask:0xf bank_mask:0xf
	v_mov_b32_dpp v160, v132 row_shr:2 row_mask:0xf bank_mask:0xf
	v_mov_b32_dpp v159, v149 row_shl:15 row_mask:0xf bank_mask:0xf
	v_mov_b32_dpp v161, v133 row_shr:2 row_mask:0xf bank_mask:0xf
	v_pk_fma_f32 v[146:147], v[78:79], v[152:153], v[146:147]
	v_mov_b32_dpp v158, v132 row_shr:1 row_mask:0xf bank_mask:0xf
	v_mov_b32_dpp v159, v133 row_shr:1 row_mask:0xf bank_mask:0xf
	v_pk_fma_f32 v[148:149], v[76:77], v[160:161], v[88:89]
	v_pk_fma_f32 v[146:147], v[130:131], v[82:83], v[146:147]
	v_pk_fma_f32 v[148:149], v[80:81], v[158:159], v[148:149]
	v_pk_mul_f32 v[152:153], v[146:147], s[60:61] op_sel_hi:[1,0]
	v_pk_fma_f32 v[148:149], v[132:133], v[84:85], v[148:149]
	v_exp_f32_e32 v152, v152
	v_exp_f32_e32 v153, v153
	v_pk_mul_f32 v[158:159], v[148:149], s[60:61] op_sel_hi:[1,0]
	v_pk_mul_f32 v[144:145], v[144:145], v[150:151]
	v_exp_f32_e32 v158, v158
	v_exp_f32_e32 v159, v159
	v_pk_add_f32 v[152:153], v[152:153], 1.0 op_sel_hi:[1,0]
	v_mov_b32_e32 v165, 0
	v_rcp_f32_e32 v152, v152
	v_rcp_f32_e32 v153, v153
	v_pk_add_f32 v[158:159], v[158:159], 1.0 op_sel_hi:[1,0]
	v_pk_mul_f32 v[146:147], v[146:147], v[152:153]
	v_rcp_f32_e32 v158, v158
	v_rcp_f32_e32 v159, v159
	v_pk_mul_f32 v[146:147], v[138:139], v[146:147]
	v_pk_mul_f32 v[138:139], v[148:149], v[158:159]
	s_nop 0
	v_pk_mul_f32 v[148:149], v[140:141], v[138:139]
	v_cvt_pk_bf16_f32 v138, v142, v143
	v_cvt_pk_bf16_f32 v139, v144, v145
	v_cvt_pk_bf16_f32 v140, v146, v147
	v_cvt_pk_bf16_f32 v141, v148, v149
	v_mov_b32_dpp v146, v134 row_shl:14 row_mask:0xf bank_mask:0xf
	v_mov_b32_dpp v147, v135 row_shl:14 row_mask:0xf bank_mask:0xf
	s_nop 0
	v_mov_b32_dpp v146, v118 row_shr:2 row_mask:0xf bank_mask:0xf
	s_nop 0
	v_mov_b32_dpp v147, v119 row_shr:2 row_mask:0xf bank_mask:0xf
	v_mov_b32_dpp v144, v134 row_shl:15 row_mask:0xf bank_mask:0xf
	v_mov_b32_dpp v145, v135 row_shl:15 row_mask:0xf bank_mask:0xf
	v_pk_fma_f32 v[134:135], v[90:91], v[146:147], v[106:107]
	v_mov_b32_dpp v148, v136 row_shl:14 row_mask:0xf bank_mask:0xf
	v_mov_b32_dpp v149, v137 row_shl:14 row_mask:0xf bank_mask:0xf
	v_mov_b32_dpp v144, v118 row_shr:1 row_mask:0xf bank_mask:0xf
	v_mov_b32_dpp v145, v119 row_shr:1 row_mask:0xf bank_mask:0xf
	v_mov_b32_dpp v146, v136 row_shl:15 row_mask:0xf bank_mask:0xf
	v_mov_b32_dpp v148, v120 row_shr:2 row_mask:0xf bank_mask:0xf
	v_mov_b32_dpp v147, v137 row_shl:15 row_mask:0xf bank_mask:0xf
	v_mov_b32_dpp v149, v121 row_shr:2 row_mask:0xf bank_mask:0xf
	v_pk_fma_f32 v[134:135], v[94:95], v[144:145], v[134:135]
	v_mov_b32_dpp v146, v120 row_shr:1 row_mask:0xf bank_mask:0xf
	v_mov_b32_dpp v147, v121 row_shr:1 row_mask:0xf bank_mask:0xf
	v_pk_fma_f32 v[136:137], v[92:93], v[148:149], v[108:109]
	v_pk_fma_f32 v[134:135], v[118:119], v[98:99], v[134:135]
	v_pk_fma_f32 v[136:137], v[96:97], v[146:147], v[136:137]
	v_pk_mul_f32 v[144:145], v[134:135], s[60:61] op_sel_hi:[1,0]
	v_pk_fma_f32 v[136:137], v[120:121], v[100:101], v[136:137]
	v_exp_f32_e32 v144, v144
	v_exp_f32_e32 v145, v145
	v_pk_mul_f32 v[146:147], v[136:137], s[60:61] op_sel_hi:[1,0]
	v_or_b32_e32 v142, 16, v168
	v_exp_f32_e32 v146, v146
	v_exp_f32_e32 v147, v147
	v_pk_add_f32 v[144:145], v[144:145], 1.0 op_sel_hi:[1,0]
	v_mad_i64_i32 v[142:143], s[38:39], v142, s76, v[156:157]
	v_rcp_f32_e32 v144, v144
	v_rcp_f32_e32 v145, v145
	v_pk_add_f32 v[146:147], v[146:147], 1.0 op_sel_hi:[1,0]
	v_lshl_add_u64 v[142:143], v[142:143], 0, v[154:155]
	v_rcp_f32_e32 v146, v146
	v_rcp_f32_e32 v147, v147
	global_store_dwordx4 v[142:143], v[138:141], off
	v_pk_mul_f32 v[134:135], v[134:135], v[144:145]
	s_nop 0
	v_pk_mul_f32 v[126:127], v[126:127], v[134:135]
	v_mov_b32_dpp v138, v130 row_shl:14 row_mask:0xf bank_mask:0xf
	v_mov_b32_dpp v139, v131 row_shl:14 row_mask:0xf bank_mask:0xf
	v_pk_mul_f32 v[134:135], v[136:137], v[146:147]
	v_mov_b32_dpp v138, v110 row_shr:2 row_mask:0xf bank_mask:0xf
	v_mov_b32_dpp v139, v111 row_shr:2 row_mask:0xf bank_mask:0xf
; #define PG8_LAS __attribute__((address_space(3)))
; __device__ __forceinline__ u32x4 pack8(f32x4 v0, f32x4 v1) { u32x4 w; w.x = cvt_pk_bf16(v0[0], v0[1]); w.y = cvt_pk_bf16(v0[2], v0[3]); w.z = cvt_pk_bf16(v1[0], v1[1]); w.w = cvt_pk_bf16(v1[2], v1[3]); return w; }
;     __device__ __forceinline__ void operator()(const f32x4 (&acc)[2][2][4][2], const Unit& u, int wr, int wc, int fr, int fq) const {
;     ...
;             f32x4 P[2] = {{0.f, 0.f, 0.f, 0.f}, {0.f, 0.f, 0.f, 0.f}};
;             if (!(ai == 0 && wr == 0) && fr >= 14) { const int pai = (wr == 1) ? ai : ai - 1, pwr = (wr == 1) ? 0 : 1;
;                 const PG8_LAS float* p = X + ((pai * 2 + pwr) * 2 + (fr - 14)) * 128 + cl; P[0] = *(const PG8_LAS f32x4*)p; P[1] = *(const PG8_LAS f32x4*)(p + 4); }
; #pragma unroll
;             for (int m = 0; m < 4; ++m) {
;                 f32x4 r[2];
; #pragma unroll
;                 for (int n = 0; n < 2; ++n)
; #pragma unroll
;                     for (int h = 0; h < 2; ++h) {
;                         f32x2 cur, p1, p2;
; #pragma unroll
;                         for (int q = 0; q < 2; ++q) { const int i = 2 * h + q;
;                             const float c_ = acc[ai][0][m][n][i], prev = (m == 0) ? P[n][i] : acc[ai][0][m == 0 ? 0 : m - 1][n][i];
;                             cur[q] = c_; p1[q] = dpp_ctl_shr1(dpp_ctl_shl15(prev), c_); p2[q] = dpp_ctl_shr2(dpp_ctl_shl14(prev), c_); }
;                         const f32x2 kb2 = {kb[n][2 * h], kb[n][2 * h + 1]}, k02 = {k0[n][2 * h], k0[n][2 * h + 1]}, k12 = {k1[n][2 * h], k1[n][2 * h + 1]}, k22 = {k2[n][2 * h], k2[n][2 * h + 1]};
;                         const f32x2 up2 = {acc[ai][1][m][n][2 * h], acc[ai][1][m][n][2 * h + 1]};
;                         const f32x2 cv = kb2 + k02 * p2 + k12 * p1 + k22 * cur;
;                         const f32x2 ex = cv * (-1.4426950408889634f);
;                         f32x2 den; den.x = __builtin_amdgcn_exp2f(ex.x); den.y = __builtin_amdgcn_exp2f(ex.y); den = den + 1.0f;
;                         f32x2 rc; rc.x = __builtin_amdgcn_rcpf(den.x); rc.y = __builtin_amdgcn_rcpf(den.y);
;                         const f32x2 o = (cv * rc) * up2;
;                         r[n][2 * h] = o.x; r[n][2 * h + 1] = o.y;
;                     }
;                 *(u32x4*)(ACT + (size_t)(row0 + ai * HALF + m * 16) * 2816 + f0) = pack8(r[0], r[1]);
	v_mov_b32_dpp v136, v130 row_shl:15 row_mask:0xf bank_mask:0xf
	v_mov_b32_dpp v137, v131 row_shl:15 row_mask:0xf bank_mask:0xf
	v_pk_fma_f32 v[130:131], v[74:75], v[138:139], v[86:87]
	v_mov_b32_dpp v140, v132 row_shl:14 row_mask:0xf bank_mask:0xf
	v_mov_b32_dpp v141, v133 row_shl:14 row_mask:0xf bank_mask:0xf
	v_mov_b32_dpp v136, v110 row_shr:1 row_mask:0xf bank_mask:0xf
	v_mov_b32_dpp v137, v111 row_shr:1 row_mask:0xf bank_mask:0xf
	v_mov_b32_dpp v138, v132 row_shl:15 row_mask:0xf bank_mask:0xf
	v_mov_b32_dpp v140, v112 row_shr:2 row_mask:0xf bank_mask:0xf
	v_mov_b32_dpp v139, v133 row_shl:15 row_mask:0xf bank_mask:0xf
	v_mov_b32_dpp v141, v113 row_shr:2 row_mask:0xf bank_mask:0xf
	v_pk_fma_f32 v[130:131], v[78:79], v[136:137], v[130:131]
	v_mov_b32_dpp v138, v112 row_shr:1 row_mask:0xf bank_mask:0xf
	v_mov_b32_dpp v139, v113 row_shr:1 row_mask:0xf bank_mask:0xf
	v_pk_fma_f32 v[132:133], v[76:77], v[140:141], v[88:89]
	v_pk_fma_f32 v[130:131], v[110:111], v[82:83], v[130:131]
	v_pk_fma_f32 v[132:133], v[80:81], v[138:139], v[132:133]
	v_pk_mul_f32 v[136:137], v[130:131], s[60:61] op_sel_hi:[1,0]
	v_pk_fma_f32 v[132:133], v[112:113], v[84:85], v[132:133]
	v_exp_f32_e32 v136, v136
	v_exp_f32_e32 v137, v137
	v_pk_mul_f32 v[138:139], v[132:133], s[60:61] op_sel_hi:[1,0]
	v_pk_mul_f32 v[128:129], v[128:129], v[134:135]
	v_exp_f32_e32 v138, v138
	v_exp_f32_e32 v139, v139
	v_pk_add_f32 v[136:137], v[136:137], 1.0 op_sel_hi:[1,0]
	v_pk_add_f32 v[138:139], v[138:139], 1.0 op_sel_hi:[1,0]
	v_rcp_f32_e32 v136, v136
	v_rcp_f32_e32 v137, v137
	v_rcp_f32_e32 v138, v138
	v_rcp_f32_e32 v139, v139
	v_pk_mul_f32 v[130:131], v[130:131], v[136:137]
	s_nop 0
	v_pk_mul_f32 v[130:131], v[122:123], v[130:131]
	v_pk_mul_f32 v[122:123], v[132:133], v[138:139]
	s_nop 0
	v_pk_mul_f32 v[132:133], v[124:125], v[122:123]
	v_cvt_pk_bf16_f32 v122, v126, v127
	v_cvt_pk_bf16_f32 v123, v128, v129
	v_cvt_pk_bf16_f32 v124, v130, v131
	v_mov_b32_dpp v130, v118 row_shl:14 row_mask:0xf bank_mask:0xf
	v_mov_b32_dpp v131, v119 row_shl:14 row_mask:0xf bank_mask:0xf
	v_mov_b32_dpp v128, v118 row_shl:15 row_mask:0xf bank_mask:0xf
	v_mov_b32_dpp v130, v114 row_shr:2 row_mask:0xf bank_mask:0xf
	v_mov_b32_dpp v129, v119 row_shl:15 row_mask:0xf bank_mask:0xf
	v_mov_b32_dpp v131, v115 row_shr:2 row_mask:0xf bank_mask:0xf
	v_mov_b32_dpp v128, v114 row_shr:1 row_mask:0xf bank_mask:0xf
	v_mov_b32_dpp v129, v115 row_shr:1 row_mask:0xf bank_mask:0xf
	v_pk_fma_f32 v[118:119], v[90:91], v[130:131], v[106:107]
	v_pk_fma_f32 v[118:119], v[94:95], v[128:129], v[118:119]
	v_mov_b32_dpp v130, v120 row_shl:14 row_mask:0xf bank_mask:0xf
	v_mov_b32_dpp v131, v121 row_shl:14 row_mask:0xf bank_mask:0xf
	v_mov_b32_dpp v128, v120 row_shl:15 row_mask:0xf bank_mask:0xf
	v_mov_b32_dpp v130, v116 row_shr:2 row_mask:0xf bank_mask:0xf
	v_mov_b32_dpp v129, v121 row_shl:15 row_mask:0xf bank_mask:0xf
	v_mov_b32_dpp v131, v117 row_shr:2 row_mask:0xf bank_mask:0xf
	v_mov_b32_dpp v128, v116 row_shr:1 row_mask:0xf bank_mask:0xf
	v_mov_b32_dpp v129, v117 row_shr:1 row_mask:0xf bank_mask:0xf
	v_pk_fma_f32 v[120:121], v[92:93], v[130:131], v[108:109]
	v_pk_fma_f32 v[114:115], v[114:115], v[98:99], v[118:119]
	v_pk_fma_f32 v[120:121], v[96:97], v[128:129], v[120:121]
	v_pk_mul_f32 v[118:119], v[114:115], s[60:61] op_sel_hi:[1,0]
	v_pk_fma_f32 v[116:117], v[116:117], v[100:101], v[120:121]
	v_exp_f32_e32 v118, v118
	v_exp_f32_e32 v119, v119
	v_pk_mul_f32 v[120:121], v[116:117], s[60:61] op_sel_hi:[1,0]
	v_or_b32_e32 v126, 32, v168
	v_exp_f32_e32 v120, v120
	v_exp_f32_e32 v121, v121
	v_pk_add_f32 v[118:119], v[118:119], 1.0 op_sel_hi:[1,0]
	v_mad_i64_i32 v[126:127], s[38:39], v126, s76, v[156:157]
	v_rcp_f32_e32 v118, v118
	v_rcp_f32_e32 v119, v119
	v_pk_add_f32 v[120:121], v[120:121], 1.0 op_sel_hi:[1,0]
	v_lshl_add_u64 v[126:127], v[126:127], 0, v[154:155]
	v_rcp_f32_e32 v120, v120
	v_rcp_f32_e32 v121, v121
	v_pk_mul_f32 v[114:115], v[114:115], v[118:119]
	v_pk_mul_f32 v[70:71], v[70:71], v[114:115]
	v_pk_mul_f32 v[114:115], v[116:117], v[120:121]
	v_mov_b32_dpp v118, v110 row_shl:14 row_mask:0xf bank_mask:0xf
	v_mov_b32_dpp v119, v111 row_shl:14 row_mask:0xf bank_mask:0xf
	v_mov_b32_dpp v116, v110 row_shl:15 row_mask:0xf bank_mask:0xf
	v_mov_b32_dpp v118, v102 row_shr:2 row_mask:0xf bank_mask:0xf
	v_mov_b32_dpp v117, v111 row_shl:15 row_mask:0xf bank_mask:0xf
	v_mov_b32_dpp v119, v103 row_shr:2 row_mask:0xf bank_mask:0xf
	v_mov_b32_dpp v116, v102 row_shr:1 row_mask:0xf bank_mask:0xf
	v_mov_b32_dpp v117, v103 row_shr:1 row_mask:0xf bank_mask:0xf
	v_pk_fma_f32 v[110:111], v[74:75], v[118:119], v[86:87]
	v_pk_fma_f32 v[110:111], v[78:79], v[116:117], v[110:111]
	v_mov_b32_dpp v118, v112 row_shl:14 row_mask:0xf bank_mask:0xf
	v_mov_b32_dpp v119, v113 row_shl:14 row_mask:0xf bank_mask:0xf
	v_mov_b32_dpp v116, v112 row_shl:15 row_mask:0xf bank_mask:0xf
	v_mov_b32_dpp v118, v104 row_shr:2 row_mask:0xf bank_mask:0xf
	v_mov_b32_dpp v117, v113 row_shl:15 row_mask:0xf bank_mask:0xf
	v_mov_b32_dpp v119, v105 row_shr:2 row_mask:0xf bank_mask:0xf
	v_mov_b32_dpp v116, v104 row_shr:1 row_mask:0xf bank_mask:0xf
	v_mov_b32_dpp v117, v105 row_shr:1 row_mask:0xf bank_mask:0xf
	v_pk_fma_f32 v[112:113], v[76:77], v[118:119], v[88:89]
	v_pk_fma_f32 v[102:103], v[102:103], v[82:83], v[110:111]
	v_pk_fma_f32 v[112:113], v[80:81], v[116:117], v[112:113]
	v_pk_mul_f32 v[110:111], v[102:103], s[60:61] op_sel_hi:[1,0]
	v_pk_fma_f32 v[104:105], v[104:105], v[84:85], v[112:113]
	v_exp_f32_e32 v110, v110
	v_exp_f32_e32 v111, v111
	v_pk_mul_f32 v[112:113], v[104:105], s[60:61] op_sel_hi:[1,0]
	v_cvt_pk_bf16_f32 v125, v132, v133
	global_store_dwordx4 v[126:127], v[122:125], off
	v_exp_f32_e32 v112, v112
	v_exp_f32_e32 v113, v113
	v_pk_add_f32 v[110:111], v[110:111], 1.0 op_sel_hi:[1,0]
	v_pk_mul_f32 v[72:73], v[72:73], v[114:115]
	v_rcp_f32_e32 v110, v110
	v_rcp_f32_e32 v111, v111
	v_pk_add_f32 v[112:113], v[112:113], 1.0 op_sel_hi:[1,0]
	v_pk_mul_f32 v[102:103], v[102:103], v[110:111]
	v_rcp_f32_e32 v112, v112
	v_rcp_f32_e32 v113, v113
	v_pk_mul_f32 v[102:103], v[66:67], v[102:103]
	v_pk_mul_f32 v[66:67], v[104:105], v[112:113]
	s_nop 0
	v_pk_mul_f32 v[104:105], v[68:69], v[66:67]
	v_cvt_pk_bf16_f32 v66, v70, v71
	v_or_b32_e32 v70, 48, v168
	v_mad_i64_i32 v[70:71], s[38:39], v70, s76, v[156:157]
	v_cvt_pk_bf16_f32 v67, v72, v73
	v_cvt_pk_bf16_f32 v68, v102, v103
	v_cvt_pk_bf16_f32 v69, v104, v105
	v_lshl_add_u64 v[70:71], v[70:71], 0, v[154:155]
	global_store_dwordx4 v[70:71], v[66:69], off
	s_nop 1
	v_mov_b32_e32 v66, 0
	v_mov_b32_e32 v67, 0
	v_mov_b32_e32 v68, 0
	v_mov_b32_e32 v69, 0
	s_and_saveexec_b64 s[38:39], s[6:7]
	s_cbranch_execz .LBB0_846
	ds_read_b128 v[162:165], v208
	ds_read_b128 v[66:69], v208 offset:16
; #define PG8_LAS __attribute__((address_space(3)))
;     __device__ __forceinline__ void operator()(const f32x4 (&acc)[2][2][4][2], const Unit& u, int wr, int wc, int fr, int fq) const {
;     ...
;         const int row0 = u.pm * BM + wr * 64 + fr;
; #pragma unroll
;         for (int ai = 0; ai < 2; ++ai) {
;             f32x4 P[2] = {{0.f, 0.f, 0.f, 0.f}, {0.f, 0.f, 0.f, 0.f}};
;             if (!(ai == 0 && wr == 0) && fr >= 14) { const int pai = (wr == 1) ? ai : ai - 1, pwr = (wr == 1) ? 0 : 1;
;                 const PG8_LAS float* p = X + ((pai * 2 + pwr) * 2 + (fr - 14)) * 128 + cl; P[0] = *(const PG8_LAS f32x4*)p; P[1] = *(const PG8_LAS f32x4*)(p + 4); }
; #pragma unroll
;             for (int m = 0; m < 4; ++m) {
;                 f32x4 r[2];
; #pragma unroll
;                 for (int n = 0; n < 2; ++n)
; #pragma unroll
;                     for (int h = 0; h < 2; ++h) {
;                         f32x2 cur, p1, p2;
; #pragma unroll
;                         for (int q = 0; q < 2; ++q) { const int i = 2 * h + q;
;                             const float c_ = acc[ai][0][m][n][i], prev = (m == 0) ? P[n][i] : acc[ai][0][m == 0 ? 0 : m - 1][n][i];
;                             cur[q] = c_; p1[q] = dpp_ctl_shr1(dpp_ctl_shl15(prev), c_); p2[q] = dpp_ctl_shr2(dpp_ctl_shl14(prev), c_); }
;                         const f32x2 kb2 = {kb[n][2 * h], kb[n][2 * h + 1]}, k02 = {k0[n][2 * h], k0[n][2 * h + 1]}, k12 = {k1[n][2 * h], k1[n][2 * h + 1]}, k22 = {k2[n][2 * h], k2[n][2 * h + 1]};
;                         const f32x2 up2 = {acc[ai][1][m][n][2 * h], acc[ai][1][m][n][2 * h + 1]};
;                         const f32x2 cv = kb2 + k02 * p2 + k12 * p1 + k22 * cur;
;                         const f32x2 ex = cv * (-1.4426950408889634f);
;                         f32x2 den; den.x = __builtin_amdgcn_exp2f(ex.x); den.y = __builtin_amdgcn_exp2f(ex.y); den = den + 1.0f;
;                         f32x2 rc; rc.x = __builtin_amdgcn_rcpf(den.x); rc.y = __builtin_amdgcn_rcpf(den.y);
;                         const f32x2 o = (cv * rc) * up2;
;                         r[n][2 * h] = o.x; r[n][2 * h + 1] = o.y;
;                     }
;                 *(u32x4*)(ACT + (size_t)(row0 + ai * HALF + m * 16) * 2816 + f0) = pack8(r[0], r[1]);
;             }
.LBB0_846:
	s_or_b64 exec, exec, s[38:39]
	s_waitcnt lgkmcnt(1)
	v_mov_b32_dpp v72, v162 row_shl:14 row_mask:0xf bank_mask:0xf
	v_mov_b32_dpp v73, v163 row_shl:14 row_mask:0xf bank_mask:0xf
	v_mov_b32_dpp v70, v162 row_shl:15 row_mask:0xf bank_mask:0xf
	v_mov_b32_dpp v72, v54 row_shr:2 row_mask:0xf bank_mask:0xf
	v_mov_b32_dpp v71, v163 row_shl:15 row_mask:0xf bank_mask:0xf
	v_mov_b32_dpp v73, v55 row_shr:2 row_mask:0xf bank_mask:0xf
	v_mov_b32_dpp v104, v164 row_shl:14 row_mask:0xf bank_mask:0xf
	v_mov_b32_dpp v105, v165 row_shl:14 row_mask:0xf bank_mask:0xf
	v_mov_b32_dpp v70, v54 row_shr:1 row_mask:0xf bank_mask:0xf
	v_mov_b32_dpp v71, v55 row_shr:1 row_mask:0xf bank_mask:0xf
	v_pk_fma_f32 v[72:73], v[90:91], v[72:73], v[106:107]
	v_mov_b32_dpp v102, v164 row_shl:15 row_mask:0xf bank_mask:0xf
	v_mov_b32_dpp v104, v56 row_shr:2 row_mask:0xf bank_mask:0xf
	v_mov_b32_dpp v103, v165 row_shl:15 row_mask:0xf bank_mask:0xf
	v_mov_b32_dpp v105, v57 row_shr:2 row_mask:0xf bank_mask:0xf
	v_pk_fma_f32 v[70:71], v[94:95], v[70:71], v[72:73]
	v_mov_b32_dpp v102, v56 row_shr:1 row_mask:0xf bank_mask:0xf
	v_mov_b32_dpp v103, v57 row_shr:1 row_mask:0xf bank_mask:0xf
	v_pk_fma_f32 v[104:105], v[92:93], v[104:105], v[108:109]
	v_pk_fma_f32 v[70:71], v[54:55], v[98:99], v[70:71]
	v_pk_fma_f32 v[102:103], v[96:97], v[102:103], v[104:105]
	v_pk_mul_f32 v[72:73], v[70:71], s[60:61] op_sel_hi:[1,0]
	v_pk_fma_f32 v[102:103], v[56:57], v[100:101], v[102:103]
	v_exp_f32_e32 v72, v72
	v_exp_f32_e32 v73, v73
	v_pk_mul_f32 v[104:105], v[102:103], s[60:61] op_sel_hi:[1,0]
	v_add_u32_e32 v110, 0x80, v168
	v_exp_f32_e32 v104, v104
	v_exp_f32_e32 v105, v105
	v_pk_add_f32 v[72:73], v[72:73], 1.0 op_sel_hi:[1,0]
	s_andn2_b64 vcc, exec, s[8:9]
	v_rcp_f32_e32 v72, v72
	v_rcp_f32_e32 v73, v73
	v_pk_add_f32 v[104:105], v[104:105], 1.0 op_sel_hi:[1,0]
	s_mov_b64 s[8:9], -1
	v_rcp_f32_e32 v104, v104
	v_rcp_f32_e32 v105, v105
	v_pk_mul_f32 v[70:71], v[70:71], v[72:73]
	v_pk_mul_f32 v[62:63], v[62:63], v[70:71]
	v_pk_mul_f32 v[70:71], v[102:103], v[104:105]
	s_waitcnt lgkmcnt(0)
	v_mov_b32_dpp v102, v66 row_shl:14 row_mask:0xf bank_mask:0xf
	v_mov_b32_dpp v103, v67 row_shl:14 row_mask:0xf bank_mask:0xf
	s_nop 0
	v_mov_b32_dpp v102, v50 row_shr:2 row_mask:0xf bank_mask:0xf
	s_nop 0
	v_mov_b32_dpp v103, v51 row_shr:2 row_mask:0xf bank_mask:0xf
	v_mov_b32_dpp v72, v66 row_shl:15 row_mask:0xf bank_mask:0xf
	v_mov_b32_dpp v73, v67 row_shl:15 row_mask:0xf bank_mask:0xf
	v_pk_fma_f32 v[66:67], v[74:75], v[102:103], v[86:87]
	v_mov_b32_dpp v104, v68 row_shl:14 row_mask:0xf bank_mask:0xf
	v_mov_b32_dpp v105, v69 row_shl:14 row_mask:0xf bank_mask:0xf
	v_mov_b32_dpp v72, v50 row_shr:1 row_mask:0xf bank_mask:0xf
	v_mov_b32_dpp v73, v51 row_shr:1 row_mask:0xf bank_mask:0xf
	v_mov_b32_dpp v102, v68 row_shl:15 row_mask:0xf bank_mask:0xf
	v_mov_b32_dpp v104, v52 row_shr:2 row_mask:0xf bank_mask:0xf
	v_mov_b32_dpp v103, v69 row_shl:15 row_mask:0xf bank_mask:0xf
	v_mov_b32_dpp v105, v53 row_shr:2 row_mask:0xf bank_mask:0xf
	v_pk_fma_f32 v[66:67], v[78:79], v[72:73], v[66:67]
	v_mov_b32_dpp v102, v52 row_shr:1 row_mask:0xf bank_mask:0xf
	v_mov_b32_dpp v103, v53 row_shr:1 row_mask:0xf bank_mask:0xf
	v_pk_fma_f32 v[68:69], v[76:77], v[104:105], v[88:89]
	v_pk_fma_f32 v[66:67], v[50:51], v[82:83], v[66:67]
	v_pk_fma_f32 v[68:69], v[80:81], v[102:103], v[68:69]
	v_pk_mul_f32 v[72:73], v[66:67], s[60:61] op_sel_hi:[1,0]
	v_pk_fma_f32 v[68:69], v[52:53], v[84:85], v[68:69]
	v_exp_f32_e32 v72, v72
	v_exp_f32_e32 v73, v73
	v_pk_mul_f32 v[102:103], v[68:69], s[60:61] op_sel_hi:[1,0]
	v_pk_mul_f32 v[64:65], v[64:65], v[70:71]
	v_exp_f32_e32 v102, v102
	v_exp_f32_e32 v103, v103
	v_pk_add_f32 v[72:73], v[72:73], 1.0 op_sel_hi:[1,0]
	v_rcp_f32_e32 v72, v72
	v_rcp_f32_e32 v73, v73
	v_pk_add_f32 v[102:103], v[102:103], 1.0 op_sel_hi:[1,0]
	v_rcp_f32_e32 v102, v102
	v_rcp_f32_e32 v103, v103
	v_pk_mul_f32 v[66:67], v[66:67], v[72:73]
	v_mov_b32_dpp v70, v56 row_shl:14 row_mask:0xf bank_mask:0xf
	v_pk_mul_f32 v[58:59], v[58:59], v[66:67]
	v_pk_mul_f32 v[66:67], v[68:69], v[102:103]
	v_pk_mul_f32 v[66:67], v[60:61], v[66:67]
	v_mov_b32_dpp v68, v54 row_shl:14 row_mask:0xf bank_mask:0xf
	v_mov_b32_dpp v69, v55 row_shl:14 row_mask:0xf bank_mask:0xf
	v_cvt_pk_bf16_f32 v60, v62, v63
	v_cvt_pk_bf16_f32 v61, v64, v65
	v_cvt_pk_bf16_f32 v62, v58, v59
	v_cvt_pk_bf16_f32 v63, v66, v67
	v_mov_b32_dpp v68, v38 row_shr:2 row_mask:0xf bank_mask:0xf
	v_mov_b32_dpp v69, v39 row_shr:2 row_mask:0xf bank_mask:0xf
	v_mov_b32_dpp v66, v54 row_shl:15 row_mask:0xf bank_mask:0xf
	v_mov_b32_dpp v67, v55 row_shl:15 row_mask:0xf bank_mask:0xf
	v_pk_fma_f32 v[54:55], v[90:91], v[68:69], v[106:107]
	v_mov_b32_dpp v71, v57 row_shl:14 row_mask:0xf bank_mask:0xf
	v_mov_b32_dpp v66, v38 row_shr:1 row_mask:0xf bank_mask:0xf
	v_mov_b32_dpp v67, v39 row_shr:1 row_mask:0xf bank_mask:0xf
	v_mov_b32_dpp v68, v56 row_shl:15 row_mask:0xf bank_mask:0xf
	v_mov_b32_dpp v70, v40 row_shr:2 row_mask:0xf bank_mask:0xf
	v_mov_b32_dpp v69, v57 row_shl:15 row_mask:0xf bank_mask:0xf
	v_mov_b32_dpp v71, v41 row_shr:2 row_mask:0xf bank_mask:0xf
	v_pk_fma_f32 v[54:55], v[94:95], v[66:67], v[54:55]
	v_mov_b32_dpp v68, v40 row_shr:1 row_mask:0xf bank_mask:0xf
	v_mov_b32_dpp v69, v41 row_shr:1 row_mask:0xf bank_mask:0xf
	v_pk_fma_f32 v[56:57], v[92:93], v[70:71], v[108:109]
	v_pk_fma_f32 v[54:55], v[38:39], v[98:99], v[54:55]
	v_pk_fma_f32 v[56:57], v[96:97], v[68:69], v[56:57]
	v_pk_mul_f32 v[66:67], v[54:55], s[60:61] op_sel_hi:[1,0]
	v_pk_fma_f32 v[56:57], v[40:41], v[100:101], v[56:57]
	v_exp_f32_e32 v66, v66
	v_exp_f32_e32 v67, v67
	v_pk_mul_f32 v[68:69], v[56:57], s[60:61] op_sel_hi:[1,0]
; #define PG8_LAS __attribute__((address_space(3)))
;     __device__ __forceinline__ void operator()(const f32x4 (&acc)[2][2][4][2], const Unit& u, int wr, int wc, int fr, int fq) const {
;     ...
;         const int row0 = u.pm * BM + wr * 64 + fr;
; #pragma unroll
;         for (int ai = 0; ai < 2; ++ai) {
;             f32x4 P[2] = {{0.f, 0.f, 0.f, 0.f}, {0.f, 0.f, 0.f, 0.f}};
;             if (!(ai == 0 && wr == 0) && fr >= 14) { const int pai = (wr == 1) ? ai : ai - 1, pwr = (wr == 1) ? 0 : 1;
;                 const PG8_LAS float* p = X + ((pai * 2 + pwr) * 2 + (fr - 14)) * 128 + cl; P[0] = *(const PG8_LAS f32x4*)p; P[1] = *(const PG8_LAS f32x4*)(p + 4); }
; #pragma unroll
;             for (int m = 0; m < 4; ++m) {
;                 f32x4 r[2];
; #pragma unroll
;                 for (int n = 0; n < 2; ++n)
; #pragma unroll
;                     for (int h = 0; h < 2; ++h) {
;                         f32x2 cur, p1, p2;
; #pragma unroll
;                         for (int q = 0; q < 2; ++q) { const int i = 2 * h + q;
;                             const float c_ = acc[ai][0][m][n][i], prev = (m == 0) ? P[n][i] : acc[ai][0][m == 0 ? 0 : m - 1][n][i];
;                             cur[q] = c_; p1[q] = dpp_ctl_shr1(dpp_ctl_shl15(prev), c_); p2[q] = dpp_ctl_shr2(dpp_ctl_shl14(prev), c_); }
;                         const f32x2 kb2 = {kb[n][2 * h], kb[n][2 * h + 1]}, k02 = {k0[n][2 * h], k0[n][2 * h + 1]}, k12 = {k1[n][2 * h], k1[n][2 * h + 1]}, k22 = {k2[n][2 * h], k2[n][2 * h + 1]};
;                         const f32x2 up2 = {acc[ai][1][m][n][2 * h], acc[ai][1][m][n][2 * h + 1]};
;                         const f32x2 cv = kb2 + k02 * p2 + k12 * p1 + k22 * cur;
;                         const f32x2 ex = cv * (-1.4426950408889634f);
;                         f32x2 den; den.x = __builtin_amdgcn_exp2f(ex.x); den.y = __builtin_amdgcn_exp2f(ex.y); den = den + 1.0f;
;                         f32x2 rc; rc.x = __builtin_amdgcn_rcpf(den.x); rc.y = __builtin_amdgcn_rcpf(den.y);
;                         const f32x2 o = (cv * rc) * up2;
;                         r[n][2 * h] = o.x; r[n][2 * h + 1] = o.y;
;                     }
;                 *(u32x4*)(ACT + (size_t)(row0 + ai * HALF + m * 16) * 2816 + f0) = pack8(r[0], r[1]);
;             }
	v_mov_b64_e32 v[58:59], s[18:19]
	v_exp_f32_e32 v68, v68
	v_exp_f32_e32 v69, v69
	v_pk_add_f32 v[66:67], v[66:67], 1.0 op_sel_hi:[1,0]
	v_mad_i64_i32 v[64:65], s[38:39], v110, s76, v[58:59]
	v_rcp_f32_e32 v66, v66
	v_rcp_f32_e32 v67, v67
	v_pk_add_f32 v[68:69], v[68:69], 1.0 op_sel_hi:[1,0]
	v_lshl_add_u64 v[64:65], v[64:65], 0, v[154:155]
	v_rcp_f32_e32 v68, v68
	v_rcp_f32_e32 v69, v69
	global_store_dwordx4 v[64:65], v[60:63], off
	v_pk_mul_f32 v[54:55], v[54:55], v[66:67]
	s_nop 0
	v_pk_mul_f32 v[46:47], v[46:47], v[54:55]
	v_mov_b32_dpp v60, v50 row_shl:14 row_mask:0xf bank_mask:0xf
	v_mov_b32_dpp v61, v51 row_shl:14 row_mask:0xf bank_mask:0xf
	v_pk_mul_f32 v[54:55], v[56:57], v[68:69]
	v_mov_b32_dpp v60, v34 row_shr:2 row_mask:0xf bank_mask:0xf
	v_mov_b32_dpp v61, v35 row_shr:2 row_mask:0xf bank_mask:0xf
	v_mov_b32_dpp v56, v50 row_shl:15 row_mask:0xf bank_mask:0xf
	v_mov_b32_dpp v57, v51 row_shl:15 row_mask:0xf bank_mask:0xf
	v_pk_fma_f32 v[50:51], v[74:75], v[60:61], v[86:87]
	v_mov_b32_dpp v62, v52 row_shl:14 row_mask:0xf bank_mask:0xf
	v_mov_b32_dpp v63, v53 row_shl:14 row_mask:0xf bank_mask:0xf
	v_mov_b32_dpp v56, v34 row_shr:1 row_mask:0xf bank_mask:0xf
	v_mov_b32_dpp v57, v35 row_shr:1 row_mask:0xf bank_mask:0xf
	v_mov_b32_dpp v60, v52 row_shl:15 row_mask:0xf bank_mask:0xf
	v_mov_b32_dpp v62, v36 row_shr:2 row_mask:0xf bank_mask:0xf
	v_mov_b32_dpp v61, v53 row_shl:15 row_mask:0xf bank_mask:0xf
	v_mov_b32_dpp v63, v37 row_shr:2 row_mask:0xf bank_mask:0xf
	v_pk_fma_f32 v[50:51], v[78:79], v[56:57], v[50:51]
	v_mov_b32_dpp v60, v36 row_shr:1 row_mask:0xf bank_mask:0xf
	v_mov_b32_dpp v61, v37 row_shr:1 row_mask:0xf bank_mask:0xf
	v_pk_fma_f32 v[52:53], v[76:77], v[62:63], v[88:89]
	v_pk_fma_f32 v[50:51], v[34:35], v[82:83], v[50:51]
	v_pk_fma_f32 v[52:53], v[80:81], v[60:61], v[52:53]
	v_pk_mul_f32 v[56:57], v[50:51], s[60:61] op_sel_hi:[1,0]
	v_pk_fma_f32 v[52:53], v[36:37], v[84:85], v[52:53]
	v_exp_f32_e32 v56, v56
	v_exp_f32_e32 v57, v57
	v_pk_mul_f32 v[60:61], v[52:53], s[60:61] op_sel_hi:[1,0]
	v_pk_mul_f32 v[48:49], v[48:49], v[54:55]
	v_exp_f32_e32 v60, v60
	v_exp_f32_e32 v61, v61
	v_pk_add_f32 v[56:57], v[56:57], 1.0 op_sel_hi:[1,0]
	v_pk_add_f32 v[60:61], v[60:61], 1.0 op_sel_hi:[1,0]
	v_rcp_f32_e32 v56, v56
	v_rcp_f32_e32 v57, v57
	v_rcp_f32_e32 v60, v60
	v_rcp_f32_e32 v61, v61
	v_pk_mul_f32 v[50:51], v[50:51], v[56:57]
	s_nop 0
	v_pk_mul_f32 v[50:51], v[42:43], v[50:51]
	v_pk_mul_f32 v[42:43], v[52:53], v[60:61]
	s_nop 0
	v_pk_mul_f32 v[52:53], v[44:45], v[42:43]
	v_cvt_pk_bf16_f32 v42, v46, v47
	v_cvt_pk_bf16_f32 v43, v48, v49
	v_cvt_pk_bf16_f32 v44, v50, v51
	v_cvt_pk_bf16_f32 v45, v52, v53
	v_mov_b32_dpp v50, v38 row_shl:14 row_mask:0xf bank_mask:0xf
	v_mov_b32_dpp v51, v39 row_shl:14 row_mask:0xf bank_mask:0xf
	s_nop 0
	v_mov_b32_dpp v50, v22 row_shr:2 row_mask:0xf bank_mask:0xf
	s_nop 0
	v_mov_b32_dpp v51, v23 row_shr:2 row_mask:0xf bank_mask:0xf
	v_mov_b32_dpp v48, v38 row_shl:15 row_mask:0xf bank_mask:0xf
	v_mov_b32_dpp v49, v39 row_shl:15 row_mask:0xf bank_mask:0xf
	v_pk_fma_f32 v[38:39], v[90:91], v[50:51], v[106:107]
	v_mov_b32_dpp v52, v40 row_shl:14 row_mask:0xf bank_mask:0xf
	v_mov_b32_dpp v53, v41 row_shl:14 row_mask:0xf bank_mask:0xf
	v_mov_b32_dpp v48, v22 row_shr:1 row_mask:0xf bank_mask:0xf
	v_mov_b32_dpp v49, v23 row_shr:1 row_mask:0xf bank_mask:0xf
	v_mov_b32_dpp v50, v40 row_shl:15 row_mask:0xf bank_mask:0xf
	v_mov_b32_dpp v52, v24 row_shr:2 row_mask:0xf bank_mask:0xf
	v_mov_b32_dpp v51, v41 row_shl:15 row_mask:0xf bank_mask:0xf
	v_mov_b32_dpp v53, v25 row_shr:2 row_mask:0xf bank_mask:0xf
	v_pk_fma_f32 v[38:39], v[94:95], v[48:49], v[38:39]
	v_mov_b32_dpp v50, v24 row_shr:1 row_mask:0xf bank_mask:0xf
	v_mov_b32_dpp v51, v25 row_shr:1 row_mask:0xf bank_mask:0xf
	v_pk_fma_f32 v[40:41], v[92:93], v[52:53], v[108:109]
	v_pk_fma_f32 v[38:39], v[22:23], v[98:99], v[38:39]
	v_pk_fma_f32 v[40:41], v[96:97], v[50:51], v[40:41]
	v_pk_mul_f32 v[48:49], v[38:39], s[60:61] op_sel_hi:[1,0]
	v_pk_fma_f32 v[40:41], v[24:25], v[100:101], v[40:41]
	v_exp_f32_e32 v48, v48
	v_exp_f32_e32 v49, v49
	v_pk_mul_f32 v[50:51], v[40:41], s[60:61] op_sel_hi:[1,0]
	v_add_u32_e32 v46, 0x90, v168
	v_exp_f32_e32 v50, v50
	v_exp_f32_e32 v51, v51
	v_pk_add_f32 v[48:49], v[48:49], 1.0 op_sel_hi:[1,0]
	v_mad_i64_i32 v[46:47], s[38:39], v46, s76, v[58:59]
	v_rcp_f32_e32 v48, v48
	v_rcp_f32_e32 v49, v49
	v_pk_add_f32 v[50:51], v[50:51], 1.0 op_sel_hi:[1,0]
	v_lshl_add_u64 v[46:47], v[46:47], 0, v[154:155]
	v_rcp_f32_e32 v50, v50
	v_rcp_f32_e32 v51, v51
	global_store_dwordx4 v[46:47], v[42:45], off
	v_pk_mul_f32 v[38:39], v[38:39], v[48:49]
	s_nop 0
	v_pk_mul_f32 v[30:31], v[30:31], v[38:39]
	v_mov_b32_dpp v42, v34 row_shl:14 row_mask:0xf bank_mask:0xf
	v_mov_b32_dpp v43, v35 row_shl:14 row_mask:0xf bank_mask:0xf
	v_pk_mul_f32 v[38:39], v[40:41], v[50:51]
	v_mov_b32_dpp v42, v14 row_shr:2 row_mask:0xf bank_mask:0xf
	v_mov_b32_dpp v43, v15 row_shr:2 row_mask:0xf bank_mask:0xf
	v_mov_b32_dpp v40, v34 row_shl:15 row_mask:0xf bank_mask:0xf
	v_mov_b32_dpp v41, v35 row_shl:15 row_mask:0xf bank_mask:0xf
	v_pk_fma_f32 v[34:35], v[74:75], v[42:43], v[86:87]
	v_mov_b32_dpp v44, v36 row_shl:14 row_mask:0xf bank_mask:0xf
	v_mov_b32_dpp v45, v37 row_shl:14 row_mask:0xf bank_mask:0xf
	v_mov_b32_dpp v40, v14 row_shr:1 row_mask:0xf bank_mask:0xf
	v_mov_b32_dpp v41, v15 row_shr:1 row_mask:0xf bank_mask:0xf
	v_mov_b32_dpp v42, v36 row_shl:15 row_mask:0xf bank_mask:0xf
	v_mov_b32_dpp v44, v16 row_shr:2 row_mask:0xf bank_mask:0xf
	v_mov_b32_dpp v43, v37 row_shl:15 row_mask:0xf bank_mask:0xf
; #define PG8_LAS __attribute__((address_space(3)))
;     __device__ __forceinline__ void operator()(const f32x4 (&acc)[2][2][4][2], const Unit& u, int wr, int wc, int fr, int fq) const {
;     ...
;         const int row0 = u.pm * BM + wr * 64 + fr;
; #pragma unroll
;         for (int ai = 0; ai < 2; ++ai) {
;             f32x4 P[2] = {{0.f, 0.f, 0.f, 0.f}, {0.f, 0.f, 0.f, 0.f}};
;             if (!(ai == 0 && wr == 0) && fr >= 14) { const int pai = (wr == 1) ? ai : ai - 1, pwr = (wr == 1) ? 0 : 1;
;                 const PG8_LAS float* p = X + ((pai * 2 + pwr) * 2 + (fr - 14)) * 128 + cl; P[0] = *(const PG8_LAS f32x4*)p; P[1] = *(const PG8_LAS f32x4*)(p + 4); }
; #pragma unroll
;             for (int m = 0; m < 4; ++m) {
;                 f32x4 r[2];
; #pragma unroll
;                 for (int n = 0; n < 2; ++n)
; #pragma unroll
;                     for (int h = 0; h < 2; ++h) {
;                         f32x2 cur, p1, p2;
; #pragma unroll
;                         for (int q = 0; q < 2; ++q) { const int i = 2 * h + q;
;                             const float c_ = acc[ai][0][m][n][i], prev = (m == 0) ? P[n][i] : acc[ai][0][m == 0 ? 0 : m - 1][n][i];
;                             cur[q] = c_; p1[q] = dpp_ctl_shr1(dpp_ctl_shl15(prev), c_); p2[q] = dpp_ctl_shr2(dpp_ctl_shl14(prev), c_); }
;                         const f32x2 kb2 = {kb[n][2 * h], kb[n][2 * h + 1]}, k02 = {k0[n][2 * h], k0[n][2 * h + 1]}, k12 = {k1[n][2 * h], k1[n][2 * h + 1]}, k22 = {k2[n][2 * h], k2[n][2 * h + 1]};
;                         const f32x2 up2 = {acc[ai][1][m][n][2 * h], acc[ai][1][m][n][2 * h + 1]};
;                         const f32x2 cv = kb2 + k02 * p2 + k12 * p1 + k22 * cur;
;                         const f32x2 ex = cv * (-1.4426950408889634f);
;                         f32x2 den; den.x = __builtin_amdgcn_exp2f(ex.x); den.y = __builtin_amdgcn_exp2f(ex.y); den = den + 1.0f;
;                         f32x2 rc; rc.x = __builtin_amdgcn_rcpf(den.x); rc.y = __builtin_amdgcn_rcpf(den.y);
;                         const f32x2 o = (cv * rc) * up2;
;                         r[n][2 * h] = o.x; r[n][2 * h + 1] = o.y;
;                     }
;                 *(u32x4*)(ACT + (size_t)(row0 + ai * HALF + m * 16) * 2816 + f0) = pack8(r[0], r[1]);
;             }
	v_mov_b32_dpp v45, v17 row_shr:2 row_mask:0xf bank_mask:0xf
	v_pk_fma_f32 v[34:35], v[78:79], v[40:41], v[34:35]
	v_mov_b32_dpp v42, v16 row_shr:1 row_mask:0xf bank_mask:0xf
	v_mov_b32_dpp v43, v17 row_shr:1 row_mask:0xf bank_mask:0xf
	v_pk_fma_f32 v[36:37], v[76:77], v[44:45], v[88:89]
	v_pk_fma_f32 v[34:35], v[14:15], v[82:83], v[34:35]
	v_pk_fma_f32 v[36:37], v[80:81], v[42:43], v[36:37]
	v_pk_mul_f32 v[40:41], v[34:35], s[60:61] op_sel_hi:[1,0]
	v_pk_fma_f32 v[36:37], v[16:17], v[84:85], v[36:37]
	v_exp_f32_e32 v40, v40
	v_exp_f32_e32 v41, v41
	v_pk_mul_f32 v[42:43], v[36:37], s[60:61] op_sel_hi:[1,0]
	v_pk_mul_f32 v[32:33], v[32:33], v[38:39]
	v_exp_f32_e32 v42, v42
	v_exp_f32_e32 v43, v43
	v_pk_add_f32 v[40:41], v[40:41], 1.0 op_sel_hi:[1,0]
	v_pk_add_f32 v[42:43], v[42:43], 1.0 op_sel_hi:[1,0]
	v_rcp_f32_e32 v40, v40
	v_rcp_f32_e32 v41, v41
	v_rcp_f32_e32 v42, v42
	v_rcp_f32_e32 v43, v43
	v_pk_mul_f32 v[34:35], v[34:35], v[40:41]
	s_nop 0
	v_pk_mul_f32 v[34:35], v[26:27], v[34:35]
	v_pk_mul_f32 v[26:27], v[36:37], v[42:43]
	s_nop 0
	v_pk_mul_f32 v[36:37], v[28:29], v[26:27]
	v_cvt_pk_bf16_f32 v26, v30, v31
	v_add_u32_e32 v30, 0xa0, v168
	v_mad_i64_i32 v[30:31], s[38:39], v30, s76, v[58:59]
	v_cvt_pk_bf16_f32 v27, v32, v33
	v_cvt_pk_bf16_f32 v28, v34, v35
	v_cvt_pk_bf16_f32 v29, v36, v37
	v_lshl_add_u64 v[30:31], v[30:31], 0, v[154:155]
	global_store_dwordx4 v[30:31], v[26:29], off
	v_mov_b32_dpp v26, v22 row_shl:15 row_mask:0xf bank_mask:0xf
	v_mov_b32_dpp v28, v22 row_shl:14 row_mask:0xf bank_mask:0xf
	v_mov_b32_dpp v27, v23 row_shl:15 row_mask:0xf bank_mask:0xf
	v_mov_b32_dpp v29, v23 row_shl:14 row_mask:0xf bank_mask:0xf
	v_mov_b32_dpp v22, v24 row_shl:15 row_mask:0xf bank_mask:0xf
	v_mov_b32_dpp v30, v24 row_shl:14 row_mask:0xf bank_mask:0xf
	v_mov_b32_dpp v23, v25 row_shl:15 row_mask:0xf bank_mask:0xf
	v_mov_b32_dpp v31, v25 row_shl:14 row_mask:0xf bank_mask:0xf
	v_mov_b32_dpp v32, v14 row_shl:14 row_mask:0xf bank_mask:0xf
	v_mov_b32_dpp v33, v15 row_shl:14 row_mask:0xf bank_mask:0xf
	v_mov_b32_dpp v24, v14 row_shl:15 row_mask:0xf bank_mask:0xf
	v_mov_b32_dpp v32, v10 row_shr:2 row_mask:0xf bank_mask:0xf
	v_mov_b32_dpp v25, v15 row_shl:15 row_mask:0xf bank_mask:0xf
	v_mov_b32_dpp v33, v11 row_shr:2 row_mask:0xf bank_mask:0xf
	v_mov_b32_dpp v30, v20 row_shr:2 row_mask:0xf bank_mask:0xf
	v_mov_b32_dpp v31, v21 row_shr:2 row_mask:0xf bank_mask:0xf
	v_mov_b32_dpp v24, v10 row_shr:1 row_mask:0xf bank_mask:0xf
	v_mov_b32_dpp v25, v11 row_shr:1 row_mask:0xf bank_mask:0xf
	v_pk_fma_f32 v[32:33], v[74:75], v[32:33], v[86:87]
	v_mov_b32_dpp v22, v20 row_shr:1 row_mask:0xf bank_mask:0xf
	v_mov_b32_dpp v23, v21 row_shr:1 row_mask:0xf bank_mask:0xf
	v_pk_fma_f32 v[24:25], v[78:79], v[24:25], v[32:33]
	v_pk_fma_f32 v[30:31], v[92:93], v[30:31], v[108:109]
	v_pk_fma_f32 v[10:11], v[10:11], v[82:83], v[24:25]
	v_pk_fma_f32 v[22:23], v[96:97], v[22:23], v[30:31]
	v_pk_mul_f32 v[24:25], v[10:11], s[60:61] op_sel_hi:[1,0]
	v_pk_fma_f32 v[20:21], v[20:21], v[100:101], v[22:23]
	v_exp_f32_e32 v24, v24
	v_exp_f32_e32 v25, v25
	v_pk_mul_f32 v[22:23], v[20:21], s[60:61] op_sel_hi:[1,0]
	v_exp_f32_e32 v22, v22
	v_exp_f32_e32 v23, v23
	v_pk_add_f32 v[24:25], v[24:25], 1.0 op_sel_hi:[1,0]
	v_rcp_f32_e32 v24, v24
	v_rcp_f32_e32 v25, v25
	v_pk_add_f32 v[22:23], v[22:23], 1.0 op_sel_hi:[1,0]
	v_mov_b32_dpp v28, v18 row_shr:2 row_mask:0xf bank_mask:0xf
	v_rcp_f32_e32 v22, v22
	v_rcp_f32_e32 v23, v23
	v_mov_b32_dpp v29, v19 row_shr:2 row_mask:0xf bank_mask:0xf
	v_mov_b32_dpp v34, v16 row_shl:14 row_mask:0xf bank_mask:0xf
	v_pk_mul_f32 v[10:11], v[10:11], v[24:25]
	v_mov_b32_dpp v35, v17 row_shl:14 row_mask:0xf bank_mask:0xf
	v_mov_b32_dpp v26, v18 row_shr:1 row_mask:0xf bank_mask:0xf
	v_mov_b32_dpp v27, v19 row_shr:1 row_mask:0xf bank_mask:0xf
	v_mov_b32_dpp v14, v16 row_shl:15 row_mask:0xf bank_mask:0xf
	v_mov_b32_dpp v34, v12 row_shr:2 row_mask:0xf bank_mask:0xf
	v_pk_mul_f32 v[10:11], v[2:3], v[10:11]
	v_pk_mul_f32 v[2:3], v[20:21], v[22:23]
	v_pk_fma_f32 v[20:21], v[90:91], v[28:29], v[106:107]
	v_mov_b32_dpp v15, v17 row_shl:15 row_mask:0xf bank_mask:0xf
	v_mov_b32_dpp v35, v13 row_shr:2 row_mask:0xf bank_mask:0xf
	v_mov_b32_dpp v14, v12 row_shr:1 row_mask:0xf bank_mask:0xf
	v_pk_fma_f32 v[20:21], v[94:95], v[26:27], v[20:21]
	v_mov_b32_dpp v15, v13 row_shr:1 row_mask:0xf bank_mask:0xf
	v_pk_fma_f32 v[16:17], v[76:77], v[34:35], v[88:89]
	v_pk_fma_f32 v[18:19], v[18:19], v[98:99], v[20:21]
	v_pk_fma_f32 v[14:15], v[80:81], v[14:15], v[16:17]
	v_pk_mul_f32 v[20:21], v[18:19], s[60:61] op_sel_hi:[1,0]
	v_pk_fma_f32 v[12:13], v[12:13], v[84:85], v[14:15]
	v_exp_f32_e32 v20, v20
	v_exp_f32_e32 v21, v21
	v_pk_mul_f32 v[14:15], v[12:13], s[60:61] op_sel_hi:[1,0]
	v_pk_mul_f32 v[8:9], v[8:9], v[2:3]
	v_exp_f32_e32 v14, v14
	v_exp_f32_e32 v15, v15
	v_pk_add_f32 v[16:17], v[20:21], 1.0 op_sel_hi:[1,0]
	v_pk_add_f32 v[14:15], v[14:15], 1.0 op_sel_hi:[1,0]
	v_rcp_f32_e32 v16, v16
	v_rcp_f32_e32 v17, v17
	v_rcp_f32_e32 v14, v14
	v_rcp_f32_e32 v15, v15
	v_pk_mul_f32 v[2:3], v[18:19], v[16:17]
	s_nop 0
	v_pk_mul_f32 v[2:3], v[6:7], v[2:3]
	v_pk_mul_f32 v[6:7], v[12:13], v[14:15]
	v_cvt_pk_bf16_f32 v2, v2, v3
	v_cvt_pk_bf16_f32 v3, v8, v9
	s_nop 0
	v_pk_mul_f32 v[6:7], v[4:5], v[6:7]
	v_cvt_pk_bf16_f32 v4, v10, v11
	s_nop 0
	v_cvt_pk_bf16_f32 v5, v6, v7
	v_add_u32_e32 v6, 0xb0, v168
	v_mad_i64_i32 v[6:7], s[38:39], v6, s76, v[58:59]
	v_lshl_add_u64 v[6:7], v[6:7], 0, v[154:155]
	global_store_dwordx4 v[6:7], v[2:5], off
	s_cbranch_vccnz .LBB0_830
	s_and_b64 vcc, exec, s[10:11]
	s_cbranch_vccnz .LBB0_829
	s_barrier
	s_branch .LBB0_829

; #define PG8_LAS __attribute__((address_space(3)))
;     __device__ __forceinline__ void operator()(const f32x4 (&acc)[2][2][4][2], const Unit& u, int wr, int wc, int fr, int fq) const {
;     ...
;         const int row0 = u.pm * BM + wr * 64 + fr;
; #pragma unroll
;         for (int ai = 0; ai < 2; ++ai) {
;             f32x4 P[2] = {{0.f, 0.f, 0.f, 0.f}, {0.f, 0.f, 0.f, 0.f}};
;             if (!(ai == 0 && wr == 0) && fr >= 14) { const int pai = (wr == 1) ? ai : ai - 1, pwr = (wr == 1) ? 0 : 1;
;                 const PG8_LAS float* p = X + ((pai * 2 + pwr) * 2 + (fr - 14)) * 128 + cl; P[0] = *(const PG8_LAS f32x4*)p; P[1] = *(const PG8_LAS f32x4*)(p + 4); }
; #pragma unroll
;             for (int m = 0; m < 4; ++m) {
;                 f32x4 r[2];
; #pragma unroll
;                 for (int n = 0; n < 2; ++n)
; #pragma unroll
;                     for (int h = 0; h < 2; ++h) {
;                         f32x2 cur, p1, p2;
; #pragma unroll
;                         for (int q = 0; q < 2; ++q) { const int i = 2 * h + q;
;                             const float c_ = acc[ai][0][m][n][i], prev = (m == 0) ? P[n][i] : acc[ai][0][m == 0 ? 0 : m - 1][n][i];
;                             cur[q] = c_; p1[q] = dpp_ctl_shr1(dpp_ctl_shl15(prev), c_); p2[q] = dpp_ctl_shr2(dpp_ctl_shl14(prev), c_); }
;                         const f32x2 kb2 = {kb[n][2 * h], kb[n][2 * h + 1]}, k02 = {k0[n][2 * h], k0[n][2 * h + 1]}, k12 = {k1[n][2 * h], k1[n][2 * h + 1]}, k22 = {k2[n][2 * h], k2[n][2 * h + 1]};
;                         const f32x2 up2 = {acc[ai][1][m][n][2 * h], acc[ai][1][m][n][2 * h + 1]};
;                         const f32x2 cv = kb2 + k02 * p2 + k12 * p1 + k22 * cur;
;                         const f32x2 ex = cv * (-1.4426950408889634f);
;                         f32x2 den; den.x = __builtin_amdgcn_exp2f(ex.x); den.y = __builtin_amdgcn_exp2f(ex.y); den = den + 1.0f;
;                         f32x2 rc; rc.x = __builtin_amdgcn_rcpf(den.x); rc.y = __builtin_amdgcn_rcpf(den.y);
;                         const f32x2 o = (cv * rc) * up2;
;                         r[n][2 * h] = o.x; r[n][2 * h + 1] = o.y;
;                     }
;                 *(u32x4*)(ACT + (size_t)(row0 + ai * HALF + m * 16) * 2816 + f0) = pack8(r[0], r[1]);
;             }
.LBB0_1747:
	s_or_b64 exec, exec, s[60:61]
	s_waitcnt lgkmcnt(0)
	v_mov_b32_dpp v206, v168 row_shl:14 row_mask:0xf bank_mask:0xf
	v_mov_b32_dpp v207, v169 row_shl:14 row_mask:0xf bank_mask:0xf
	s_nop 0
	v_mov_b32_dpp v206, v150 row_shr:2 row_mask:0xf bank_mask:0xf
	s_nop 0
	v_mov_b32_dpp v207, v151 row_shr:2 row_mask:0xf bank_mask:0xf
	v_mov_b32_dpp v204, v168 row_shl:15 row_mask:0xf bank_mask:0xf
	v_mov_b32_dpp v205, v169 row_shl:15 row_mask:0xf bank_mask:0xf
	s_waitcnt vmcnt(0)
	v_pk_fma_f32 v[168:169], v[90:91], v[206:207], v[106:107]
	v_mov_b32_dpp v208, v170 row_shl:14 row_mask:0xf bank_mask:0xf
	v_mov_b32_dpp v209, v171 row_shl:14 row_mask:0xf bank_mask:0xf
	v_mov_b32_dpp v204, v150 row_shr:1 row_mask:0xf bank_mask:0xf
	v_mov_b32_dpp v205, v151 row_shr:1 row_mask:0xf bank_mask:0xf
	v_mov_b32_dpp v206, v170 row_shl:15 row_mask:0xf bank_mask:0xf
	v_mov_b32_dpp v208, v152 row_shr:2 row_mask:0xf bank_mask:0xf
	v_mov_b32_dpp v207, v171 row_shl:15 row_mask:0xf bank_mask:0xf
	v_mov_b32_dpp v209, v153 row_shr:2 row_mask:0xf bank_mask:0xf
	v_pk_fma_f32 v[168:169], v[94:95], v[204:205], v[168:169]
	v_mov_b32_dpp v206, v152 row_shr:1 row_mask:0xf bank_mask:0xf
	v_mov_b32_dpp v207, v153 row_shr:1 row_mask:0xf bank_mask:0xf
	v_pk_fma_f32 v[170:171], v[92:93], v[208:209], v[108:109]
	v_pk_fma_f32 v[204:205], v[150:151], v[98:99], v[168:169]
	v_pk_fma_f32 v[170:171], v[96:97], v[206:207], v[170:171]
	v_pk_mul_f32 v[168:169], v[204:205], s[48:49] op_sel_hi:[1,0]
	v_pk_fma_f32 v[170:171], v[152:153], v[100:101], v[170:171]
	v_exp_f32_e32 v168, v168
	v_exp_f32_e32 v169, v169
	v_pk_mul_f32 v[206:207], v[170:171], s[48:49] op_sel_hi:[1,0]
	v_mov_b32_e32 v163, 0
	v_exp_f32_e32 v206, v206
	v_exp_f32_e32 v207, v207
	v_pk_add_f32 v[168:169], v[168:169], 1.0 op_sel_hi:[1,0]
	s_nop 0
	v_rcp_f32_e32 v208, v168
	v_rcp_f32_e32 v209, v169
	v_pk_add_f32 v[168:169], v[206:207], 1.0 op_sel_hi:[1,0]
	v_pk_mul_f32 v[204:205], v[204:205], v[208:209]
	v_rcp_f32_e32 v206, v168
	v_rcp_f32_e32 v207, v169
	v_pk_mul_f32 v[158:159], v[158:159], v[204:205]
	v_pk_mul_f32 v[170:171], v[170:171], v[206:207]
	v_mov_b32_dpp v204, v164 row_shl:15 row_mask:0xf bank_mask:0xf
	v_mov_b32_dpp v206, v164 row_shl:14 row_mask:0xf bank_mask:0xf
	v_mov_b32_dpp v207, v165 row_shl:14 row_mask:0xf bank_mask:0xf
	v_mov_b32_dpp v205, v165 row_shl:15 row_mask:0xf bank_mask:0xf
	v_mov_b32_dpp v206, v146 row_shr:2 row_mask:0xf bank_mask:0xf
	v_mov_b32_dpp v207, v147 row_shr:2 row_mask:0xf bank_mask:0xf
	v_mov_b32_dpp v204, v146 row_shr:1 row_mask:0xf bank_mask:0xf
	v_mov_b32_dpp v205, v147 row_shr:1 row_mask:0xf bank_mask:0xf
	v_pk_fma_f32 v[164:165], v[74:75], v[206:207], v[86:87]
	v_mov_b32_dpp v208, v166 row_shl:14 row_mask:0xf bank_mask:0xf
	v_mov_b32_dpp v209, v167 row_shl:14 row_mask:0xf bank_mask:0xf
	v_pk_fma_f32 v[164:165], v[78:79], v[204:205], v[164:165]
	v_mov_b32_dpp v206, v166 row_shl:15 row_mask:0xf bank_mask:0xf
	v_mov_b32_dpp v208, v148 row_shr:2 row_mask:0xf bank_mask:0xf
	v_mov_b32_dpp v207, v167 row_shl:15 row_mask:0xf bank_mask:0xf
	v_mov_b32_dpp v209, v149 row_shr:2 row_mask:0xf bank_mask:0xf
	v_pk_fma_f32 v[164:165], v[146:147], v[82:83], v[164:165]
	v_mov_b32_dpp v206, v148 row_shr:1 row_mask:0xf bank_mask:0xf
	v_mov_b32_dpp v207, v149 row_shr:1 row_mask:0xf bank_mask:0xf
	v_pk_fma_f32 v[166:167], v[76:77], v[208:209], v[88:89]
	v_pk_mul_f32 v[204:205], v[164:165], s[48:49] op_sel_hi:[1,0]
	v_pk_fma_f32 v[166:167], v[80:81], v[206:207], v[166:167]
	v_exp_f32_e32 v204, v204
	v_exp_f32_e32 v205, v205
	v_pk_fma_f32 v[166:167], v[148:149], v[84:85], v[166:167]
	v_pk_mul_f32 v[160:161], v[160:161], v[170:171]
	v_pk_mul_f32 v[206:207], v[166:167], s[48:49] op_sel_hi:[1,0]
	v_pk_add_f32 v[204:205], v[204:205], 1.0 op_sel_hi:[1,0]
	v_exp_f32_e32 v206, v206
	v_exp_f32_e32 v207, v207
	v_rcp_f32_e32 v204, v204
	v_rcp_f32_e32 v205, v205
	v_pk_add_f32 v[206:207], v[206:207], 1.0 op_sel_hi:[1,0]
	v_rcp_f32_e32 v206, v206
	v_rcp_f32_e32 v207, v207
	v_pk_mul_f32 v[164:165], v[164:165], v[204:205]
	v_mov_b32_dpp v170, v150 row_shl:14 row_mask:0xf bank_mask:0xf
	v_pk_mul_f32 v[154:155], v[154:155], v[164:165]
	v_mov_b32_dpp v171, v151 row_shl:14 row_mask:0xf bank_mask:0xf
	v_pk_mul_f32 v[164:165], v[166:167], v[206:207]
	v_cvt_pk_bf16_f32 v158, v158, v159
	v_cvt_pk_bf16_f32 v159, v160, v161
	v_cvt_pk_bf16_f32 v160, v154, v155
	v_lshlrev_b64 v[154:155], 1, v[192:193]
	v_mov_b32_dpp v170, v134 row_shr:2 row_mask:0xf bank_mask:0xf
	v_mov_b32_dpp v171, v135 row_shr:2 row_mask:0xf bank_mask:0xf
	v_mov_b32_dpp v166, v150 row_shl:15 row_mask:0xf bank_mask:0xf
	v_mov_b32_dpp v167, v151 row_shl:15 row_mask:0xf bank_mask:0xf
	v_pk_fma_f32 v[150:151], v[90:91], v[170:171], v[106:107]
	v_mov_b32_dpp v192, v152 row_shl:14 row_mask:0xf bank_mask:0xf
	v_mov_b32_dpp v193, v153 row_shl:14 row_mask:0xf bank_mask:0xf
	v_mov_b32_dpp v166, v134 row_shr:1 row_mask:0xf bank_mask:0xf
	v_mov_b32_dpp v167, v135 row_shr:1 row_mask:0xf bank_mask:0xf
	v_mov_b32_dpp v170, v152 row_shl:15 row_mask:0xf bank_mask:0xf
	v_mov_b32_dpp v192, v136 row_shr:2 row_mask:0xf bank_mask:0xf
	v_mov_b32_dpp v171, v153 row_shl:15 row_mask:0xf bank_mask:0xf
	v_mov_b32_dpp v193, v137 row_shr:2 row_mask:0xf bank_mask:0xf
	v_pk_fma_f32 v[150:151], v[94:95], v[166:167], v[150:151]
	v_mov_b32_dpp v170, v136 row_shr:1 row_mask:0xf bank_mask:0xf
	v_mov_b32_dpp v171, v137 row_shr:1 row_mask:0xf bank_mask:0xf
	v_pk_fma_f32 v[152:153], v[92:93], v[192:193], v[108:109]
	v_pk_fma_f32 v[150:151], v[134:135], v[98:99], v[150:151]
	v_pk_fma_f32 v[152:153], v[96:97], v[170:171], v[152:153]
	v_pk_mul_f32 v[166:167], v[150:151], s[48:49] op_sel_hi:[1,0]
; #define PG8_LAS __attribute__((address_space(3)))
;     __device__ __forceinline__ void operator()(const f32x4 (&acc)[2][2][4][2], const Unit& u, int wr, int wc, int fr, int fq) const {
;     ...
;         const int row0 = u.pm * BM + wr * 64 + fr;
; #pragma unroll
;         for (int ai = 0; ai < 2; ++ai) {
;             f32x4 P[2] = {{0.f, 0.f, 0.f, 0.f}, {0.f, 0.f, 0.f, 0.f}};
;             if (!(ai == 0 && wr == 0) && fr >= 14) { const int pai = (wr == 1) ? ai : ai - 1, pwr = (wr == 1) ? 0 : 1;
;                 const PG8_LAS float* p = X + ((pai * 2 + pwr) * 2 + (fr - 14)) * 128 + cl; P[0] = *(const PG8_LAS f32x4*)p; P[1] = *(const PG8_LAS f32x4*)(p + 4); }
; #pragma unroll
;             for (int m = 0; m < 4; ++m) {
;                 f32x4 r[2];
; #pragma unroll
;                 for (int n = 0; n < 2; ++n)
; #pragma unroll
;                     for (int h = 0; h < 2; ++h) {
;                         f32x2 cur, p1, p2;
; #pragma unroll
;                         for (int q = 0; q < 2; ++q) { const int i = 2 * h + q;
;                             const float c_ = acc[ai][0][m][n][i], prev = (m == 0) ? P[n][i] : acc[ai][0][m == 0 ? 0 : m - 1][n][i];
;                             cur[q] = c_; p1[q] = dpp_ctl_shr1(dpp_ctl_shl15(prev), c_); p2[q] = dpp_ctl_shr2(dpp_ctl_shl14(prev), c_); }
;                         const f32x2 kb2 = {kb[n][2 * h], kb[n][2 * h + 1]}, k02 = {k0[n][2 * h], k0[n][2 * h + 1]}, k12 = {k1[n][2 * h], k1[n][2 * h + 1]}, k22 = {k2[n][2 * h], k2[n][2 * h + 1]};
;                         const f32x2 up2 = {acc[ai][1][m][n][2 * h], acc[ai][1][m][n][2 * h + 1]};
;                         const f32x2 cv = kb2 + k02 * p2 + k12 * p1 + k22 * cur;
;                         const f32x2 ex = cv * (-1.4426950408889634f);
;                         f32x2 den; den.x = __builtin_amdgcn_exp2f(ex.x); den.y = __builtin_amdgcn_exp2f(ex.y); den = den + 1.0f;
;                         f32x2 rc; rc.x = __builtin_amdgcn_rcpf(den.x); rc.y = __builtin_amdgcn_rcpf(den.y);
;                         const f32x2 o = (cv * rc) * up2;
;                         r[n][2 * h] = o.x; r[n][2 * h + 1] = o.y;
;                     }
;                 *(u32x4*)(ACT + (size_t)(row0 + ai * HALF + m * 16) * 2816 + f0) = pack8(r[0], r[1]);
;             }
	v_pk_fma_f32 v[152:153], v[136:137], v[100:101], v[152:153]
	v_exp_f32_e32 v166, v166
	v_exp_f32_e32 v167, v167
	v_pk_mul_f32 v[170:171], v[152:153], s[48:49] op_sel_hi:[1,0]
	v_pk_mul_f32 v[156:157], v[156:157], v[164:165]
	v_exp_f32_e32 v170, v170
	v_exp_f32_e32 v171, v171
	v_pk_add_f32 v[166:167], v[166:167], 1.0 op_sel_hi:[1,0]
	v_lshl_add_u32 v168, s58, 8, v181
	v_cvt_pk_bf16_f32 v161, v156, v157
	v_mov_b64_e32 v[156:157], s[14:15]
	v_rcp_f32_e32 v166, v166
	v_rcp_f32_e32 v167, v167
	v_pk_add_f32 v[170:171], v[170:171], 1.0 op_sel_hi:[1,0]
	v_mad_i64_i32 v[164:165], s[58:59], v168, s74, v[156:157]
	v_rcp_f32_e32 v170, v170
	v_rcp_f32_e32 v171, v171
	v_lshl_add_u64 v[164:165], v[164:165], 0, v[154:155]
	global_store_dwordx4 v[164:165], v[158:161], off
	v_pk_mul_f32 v[150:151], v[150:151], v[166:167]
	v_mov_b32_e32 v164, 0
	v_pk_mul_f32 v[142:143], v[142:143], v[150:151]
	v_mov_b32_dpp v158, v146 row_shl:14 row_mask:0xf bank_mask:0xf
	v_mov_b32_dpp v159, v147 row_shl:14 row_mask:0xf bank_mask:0xf
	v_pk_mul_f32 v[150:151], v[152:153], v[170:171]
	v_mov_b32_dpp v158, v130 row_shr:2 row_mask:0xf bank_mask:0xf
	v_mov_b32_dpp v159, v131 row_shr:2 row_mask:0xf bank_mask:0xf
	v_mov_b32_dpp v152, v146 row_shl:15 row_mask:0xf bank_mask:0xf
	v_mov_b32_dpp v153, v147 row_shl:15 row_mask:0xf bank_mask:0xf
	v_pk_fma_f32 v[146:147], v[74:75], v[158:159], v[86:87]
	v_mov_b32_dpp v160, v148 row_shl:14 row_mask:0xf bank_mask:0xf
	v_mov_b32_dpp v161, v149 row_shl:14 row_mask:0xf bank_mask:0xf
	v_mov_b32_dpp v152, v130 row_shr:1 row_mask:0xf bank_mask:0xf
	v_mov_b32_dpp v153, v131 row_shr:1 row_mask:0xf bank_mask:0xf
	v_mov_b32_dpp v158, v148 row_shl:15 row_mask:0xf bank_mask:0xf
	v_mov_b32_dpp v160, v132 row_shr:2 row_mask:0xf bank_mask:0xf
	v_mov_b32_dpp v159, v149 row_shl:15 row_mask:0xf bank_mask:0xf
	v_mov_b32_dpp v161, v133 row_shr:2 row_mask:0xf bank_mask:0xf
	v_pk_fma_f32 v[146:147], v[78:79], v[152:153], v[146:147]
	v_mov_b32_dpp v158, v132 row_shr:1 row_mask:0xf bank_mask:0xf
	v_mov_b32_dpp v159, v133 row_shr:1 row_mask:0xf bank_mask:0xf
	v_pk_fma_f32 v[148:149], v[76:77], v[160:161], v[88:89]
	v_pk_fma_f32 v[146:147], v[130:131], v[82:83], v[146:147]
	v_pk_fma_f32 v[148:149], v[80:81], v[158:159], v[148:149]
	v_pk_mul_f32 v[152:153], v[146:147], s[48:49] op_sel_hi:[1,0]
	v_pk_fma_f32 v[148:149], v[132:133], v[84:85], v[148:149]
	v_exp_f32_e32 v152, v152
	v_exp_f32_e32 v153, v153
	v_pk_mul_f32 v[158:159], v[148:149], s[48:49] op_sel_hi:[1,0]
	v_pk_mul_f32 v[144:145], v[144:145], v[150:151]
	v_exp_f32_e32 v158, v158
	v_exp_f32_e32 v159, v159
	v_pk_add_f32 v[152:153], v[152:153], 1.0 op_sel_hi:[1,0]
	v_mov_b32_e32 v165, 0
	v_rcp_f32_e32 v152, v152
	v_rcp_f32_e32 v153, v153
	v_pk_add_f32 v[158:159], v[158:159], 1.0 op_sel_hi:[1,0]
	v_pk_mul_f32 v[146:147], v[146:147], v[152:153]
	v_rcp_f32_e32 v158, v158
	v_rcp_f32_e32 v159, v159
	v_pk_mul_f32 v[146:147], v[138:139], v[146:147]
	v_pk_mul_f32 v[138:139], v[148:149], v[158:159]
	s_nop 0
	v_pk_mul_f32 v[148:149], v[140:141], v[138:139]
	v_cvt_pk_bf16_f32 v138, v142, v143
	v_cvt_pk_bf16_f32 v139, v144, v145
	v_cvt_pk_bf16_f32 v140, v146, v147
	v_cvt_pk_bf16_f32 v141, v148, v149
	v_mov_b32_dpp v146, v134 row_shl:14 row_mask:0xf bank_mask:0xf
	v_mov_b32_dpp v147, v135 row_shl:14 row_mask:0xf bank_mask:0xf
	s_nop 0
	v_mov_b32_dpp v146, v118 row_shr:2 row_mask:0xf bank_mask:0xf
	s_nop 0
	v_mov_b32_dpp v147, v119 row_shr:2 row_mask:0xf bank_mask:0xf
	v_mov_b32_dpp v144, v134 row_shl:15 row_mask:0xf bank_mask:0xf
	v_mov_b32_dpp v145, v135 row_shl:15 row_mask:0xf bank_mask:0xf
	v_pk_fma_f32 v[134:135], v[90:91], v[146:147], v[106:107]
	v_mov_b32_dpp v148, v136 row_shl:14 row_mask:0xf bank_mask:0xf
	v_mov_b32_dpp v149, v137 row_shl:14 row_mask:0xf bank_mask:0xf
	v_mov_b32_dpp v144, v118 row_shr:1 row_mask:0xf bank_mask:0xf
	v_mov_b32_dpp v145, v119 row_shr:1 row_mask:0xf bank_mask:0xf
	v_mov_b32_dpp v146, v136 row_shl:15 row_mask:0xf bank_mask:0xf
	v_mov_b32_dpp v148, v120 row_shr:2 row_mask:0xf bank_mask:0xf
	v_mov_b32_dpp v147, v137 row_shl:15 row_mask:0xf bank_mask:0xf
	v_mov_b32_dpp v149, v121 row_shr:2 row_mask:0xf bank_mask:0xf
	v_pk_fma_f32 v[134:135], v[94:95], v[144:145], v[134:135]
	v_mov_b32_dpp v146, v120 row_shr:1 row_mask:0xf bank_mask:0xf
	v_mov_b32_dpp v147, v121 row_shr:1 row_mask:0xf bank_mask:0xf
	v_pk_fma_f32 v[136:137], v[92:93], v[148:149], v[108:109]
	v_pk_fma_f32 v[134:135], v[118:119], v[98:99], v[134:135]
	v_pk_fma_f32 v[136:137], v[96:97], v[146:147], v[136:137]
	v_pk_mul_f32 v[144:145], v[134:135], s[48:49] op_sel_hi:[1,0]
	v_pk_fma_f32 v[136:137], v[120:121], v[100:101], v[136:137]
	v_exp_f32_e32 v144, v144
	v_exp_f32_e32 v145, v145
	v_pk_mul_f32 v[146:147], v[136:137], s[48:49] op_sel_hi:[1,0]
	v_or_b32_e32 v142, 16, v168
	v_exp_f32_e32 v146, v146
	v_exp_f32_e32 v147, v147
	v_pk_add_f32 v[144:145], v[144:145], 1.0 op_sel_hi:[1,0]
	v_mad_i64_i32 v[142:143], s[58:59], v142, s74, v[156:157]
	v_rcp_f32_e32 v144, v144
	v_rcp_f32_e32 v145, v145
	v_pk_add_f32 v[146:147], v[146:147], 1.0 op_sel_hi:[1,0]
	v_lshl_add_u64 v[142:143], v[142:143], 0, v[154:155]
	v_rcp_f32_e32 v146, v146
	v_rcp_f32_e32 v147, v147
	global_store_dwordx4 v[142:143], v[138:141], off
	v_pk_mul_f32 v[134:135], v[134:135], v[144:145]
	s_nop 0
	v_pk_mul_f32 v[126:127], v[126:127], v[134:135]
	v_mov_b32_dpp v138, v130 row_shl:14 row_mask:0xf bank_mask:0xf
	v_mov_b32_dpp v139, v131 row_shl:14 row_mask:0xf bank_mask:0xf
	v_pk_mul_f32 v[134:135], v[136:137], v[146:147]
	v_mov_b32_dpp v138, v110 row_shr:2 row_mask:0xf bank_mask:0xf
	v_mov_b32_dpp v139, v111 row_shr:2 row_mask:0xf bank_mask:0xf
; #define PG8_LAS __attribute__((address_space(3)))
;     __device__ __forceinline__ void operator()(const f32x4 (&acc)[2][2][4][2], const Unit& u, int wr, int wc, int fr, int fq) const {
;     ...
;         const int row0 = u.pm * BM + wr * 64 + fr;
; #pragma unroll
;         for (int ai = 0; ai < 2; ++ai) {
;             f32x4 P[2] = {{0.f, 0.f, 0.f, 0.f}, {0.f, 0.f, 0.f, 0.f}};
;             if (!(ai == 0 && wr == 0) && fr >= 14) { const int pai = (wr == 1) ? ai : ai - 1, pwr = (wr == 1) ? 0 : 1;
;                 const PG8_LAS float* p = X + ((pai * 2 + pwr) * 2 + (fr - 14)) * 128 + cl; P[0] = *(const PG8_LAS f32x4*)p; P[1] = *(const PG8_LAS f32x4*)(p + 4); }
; #pragma unroll
;             for (int m = 0; m < 4; ++m) {
;                 f32x4 r[2];
; #pragma unroll
;                 for (int n = 0; n < 2; ++n)
; #pragma unroll
;                     for (int h = 0; h < 2; ++h) {
;                         f32x2 cur, p1, p2;
; #pragma unroll
;                         for (int q = 0; q < 2; ++q) { const int i = 2 * h + q;
;                             const float c_ = acc[ai][0][m][n][i], prev = (m == 0) ? P[n][i] : acc[ai][0][m == 0 ? 0 : m - 1][n][i];
;                             cur[q] = c_; p1[q] = dpp_ctl_shr1(dpp_ctl_shl15(prev), c_); p2[q] = dpp_ctl_shr2(dpp_ctl_shl14(prev), c_); }
;                         const f32x2 kb2 = {kb[n][2 * h], kb[n][2 * h + 1]}, k02 = {k0[n][2 * h], k0[n][2 * h + 1]}, k12 = {k1[n][2 * h], k1[n][2 * h + 1]}, k22 = {k2[n][2 * h], k2[n][2 * h + 1]};
;                         const f32x2 up2 = {acc[ai][1][m][n][2 * h], acc[ai][1][m][n][2 * h + 1]};
;                         const f32x2 cv = kb2 + k02 * p2 + k12 * p1 + k22 * cur;
;                         const f32x2 ex = cv * (-1.4426950408889634f);
;                         f32x2 den; den.x = __builtin_amdgcn_exp2f(ex.x); den.y = __builtin_amdgcn_exp2f(ex.y); den = den + 1.0f;
;                         f32x2 rc; rc.x = __builtin_amdgcn_rcpf(den.x); rc.y = __builtin_amdgcn_rcpf(den.y);
;                         const f32x2 o = (cv * rc) * up2;
;                         r[n][2 * h] = o.x; r[n][2 * h + 1] = o.y;
;                     }
;                 *(u32x4*)(ACT + (size_t)(row0 + ai * HALF + m * 16) * 2816 + f0) = pack8(r[0], r[1]);
;             }
	v_mov_b32_dpp v136, v130 row_shl:15 row_mask:0xf bank_mask:0xf
	v_mov_b32_dpp v137, v131 row_shl:15 row_mask:0xf bank_mask:0xf
	v_pk_fma_f32 v[130:131], v[74:75], v[138:139], v[86:87]
	v_mov_b32_dpp v140, v132 row_shl:14 row_mask:0xf bank_mask:0xf
	v_mov_b32_dpp v141, v133 row_shl:14 row_mask:0xf bank_mask:0xf
	v_mov_b32_dpp v136, v110 row_shr:1 row_mask:0xf bank_mask:0xf
	v_mov_b32_dpp v137, v111 row_shr:1 row_mask:0xf bank_mask:0xf
	v_mov_b32_dpp v138, v132 row_shl:15 row_mask:0xf bank_mask:0xf
	v_mov_b32_dpp v140, v112 row_shr:2 row_mask:0xf bank_mask:0xf
	v_mov_b32_dpp v139, v133 row_shl:15 row_mask:0xf bank_mask:0xf
	v_mov_b32_dpp v141, v113 row_shr:2 row_mask:0xf bank_mask:0xf
	v_pk_fma_f32 v[130:131], v[78:79], v[136:137], v[130:131]
	v_mov_b32_dpp v138, v112 row_shr:1 row_mask:0xf bank_mask:0xf
	v_mov_b32_dpp v139, v113 row_shr:1 row_mask:0xf bank_mask:0xf
	v_pk_fma_f32 v[132:133], v[76:77], v[140:141], v[88:89]
	v_pk_fma_f32 v[130:131], v[110:111], v[82:83], v[130:131]
	v_pk_fma_f32 v[132:133], v[80:81], v[138:139], v[132:133]
	v_pk_mul_f32 v[136:137], v[130:131], s[48:49] op_sel_hi:[1,0]
	v_pk_fma_f32 v[132:133], v[112:113], v[84:85], v[132:133]
	v_exp_f32_e32 v136, v136
	v_exp_f32_e32 v137, v137
	v_pk_mul_f32 v[138:139], v[132:133], s[48:49] op_sel_hi:[1,0]
	v_pk_mul_f32 v[128:129], v[128:129], v[134:135]
	v_exp_f32_e32 v138, v138
	v_exp_f32_e32 v139, v139
	v_pk_add_f32 v[136:137], v[136:137], 1.0 op_sel_hi:[1,0]
	v_pk_add_f32 v[138:139], v[138:139], 1.0 op_sel_hi:[1,0]
	v_rcp_f32_e32 v136, v136
	v_rcp_f32_e32 v137, v137
	v_rcp_f32_e32 v138, v138
	v_rcp_f32_e32 v139, v139
	v_pk_mul_f32 v[130:131], v[130:131], v[136:137]
	s_nop 0
	v_pk_mul_f32 v[130:131], v[122:123], v[130:131]
	v_pk_mul_f32 v[122:123], v[132:133], v[138:139]
	s_nop 0
	v_pk_mul_f32 v[132:133], v[124:125], v[122:123]
	v_cvt_pk_bf16_f32 v122, v126, v127
	v_cvt_pk_bf16_f32 v123, v128, v129
	v_cvt_pk_bf16_f32 v124, v130, v131
	v_mov_b32_dpp v130, v118 row_shl:14 row_mask:0xf bank_mask:0xf
	v_mov_b32_dpp v131, v119 row_shl:14 row_mask:0xf bank_mask:0xf
	v_mov_b32_dpp v128, v118 row_shl:15 row_mask:0xf bank_mask:0xf
	v_mov_b32_dpp v130, v114 row_shr:2 row_mask:0xf bank_mask:0xf
	v_mov_b32_dpp v129, v119 row_shl:15 row_mask:0xf bank_mask:0xf
	v_mov_b32_dpp v131, v115 row_shr:2 row_mask:0xf bank_mask:0xf
	v_mov_b32_dpp v128, v114 row_shr:1 row_mask:0xf bank_mask:0xf
	v_mov_b32_dpp v129, v115 row_shr:1 row_mask:0xf bank_mask:0xf
	v_pk_fma_f32 v[118:119], v[90:91], v[130:131], v[106:107]
	v_pk_fma_f32 v[118:119], v[94:95], v[128:129], v[118:119]
	v_mov_b32_dpp v130, v120 row_shl:14 row_mask:0xf bank_mask:0xf
	v_mov_b32_dpp v131, v121 row_shl:14 row_mask:0xf bank_mask:0xf
	v_mov_b32_dpp v128, v120 row_shl:15 row_mask:0xf bank_mask:0xf
	v_mov_b32_dpp v130, v116 row_shr:2 row_mask:0xf bank_mask:0xf
	v_mov_b32_dpp v129, v121 row_shl:15 row_mask:0xf bank_mask:0xf
	v_mov_b32_dpp v131, v117 row_shr:2 row_mask:0xf bank_mask:0xf
	v_mov_b32_dpp v128, v116 row_shr:1 row_mask:0xf bank_mask:0xf
	v_mov_b32_dpp v129, v117 row_shr:1 row_mask:0xf bank_mask:0xf
	v_pk_fma_f32 v[120:121], v[92:93], v[130:131], v[108:109]
	v_pk_fma_f32 v[114:115], v[114:115], v[98:99], v[118:119]
	v_pk_fma_f32 v[120:121], v[96:97], v[128:129], v[120:121]
	v_pk_mul_f32 v[118:119], v[114:115], s[48:49] op_sel_hi:[1,0]
	v_pk_fma_f32 v[116:117], v[116:117], v[100:101], v[120:121]
	v_exp_f32_e32 v118, v118
	v_exp_f32_e32 v119, v119
	v_pk_mul_f32 v[120:121], v[116:117], s[48:49] op_sel_hi:[1,0]
	v_or_b32_e32 v126, 32, v168
	v_exp_f32_e32 v120, v120
	v_exp_f32_e32 v121, v121
	v_pk_add_f32 v[118:119], v[118:119], 1.0 op_sel_hi:[1,0]
	v_mad_i64_i32 v[126:127], s[58:59], v126, s74, v[156:157]
	v_rcp_f32_e32 v118, v118
	v_rcp_f32_e32 v119, v119
	v_pk_add_f32 v[120:121], v[120:121], 1.0 op_sel_hi:[1,0]
	v_lshl_add_u64 v[126:127], v[126:127], 0, v[154:155]
	v_rcp_f32_e32 v120, v120
	v_rcp_f32_e32 v121, v121
	v_pk_mul_f32 v[114:115], v[114:115], v[118:119]
	v_pk_mul_f32 v[70:71], v[70:71], v[114:115]
	v_pk_mul_f32 v[114:115], v[116:117], v[120:121]
	v_mov_b32_dpp v118, v110 row_shl:14 row_mask:0xf bank_mask:0xf
	v_mov_b32_dpp v119, v111 row_shl:14 row_mask:0xf bank_mask:0xf
	v_mov_b32_dpp v116, v110 row_shl:15 row_mask:0xf bank_mask:0xf
	v_mov_b32_dpp v118, v102 row_shr:2 row_mask:0xf bank_mask:0xf
	v_mov_b32_dpp v117, v111 row_shl:15 row_mask:0xf bank_mask:0xf
	v_mov_b32_dpp v119, v103 row_shr:2 row_mask:0xf bank_mask:0xf
	v_mov_b32_dpp v116, v102 row_shr:1 row_mask:0xf bank_mask:0xf
	v_mov_b32_dpp v117, v103 row_shr:1 row_mask:0xf bank_mask:0xf
	v_pk_fma_f32 v[110:111], v[74:75], v[118:119], v[86:87]
	v_pk_fma_f32 v[110:111], v[78:79], v[116:117], v[110:111]
	v_mov_b32_dpp v118, v112 row_shl:14 row_mask:0xf bank_mask:0xf
	v_mov_b32_dpp v119, v113 row_shl:14 row_mask:0xf bank_mask:0xf
	v_mov_b32_dpp v116, v112 row_shl:15 row_mask:0xf bank_mask:0xf
	v_mov_b32_dpp v118, v104 row_shr:2 row_mask:0xf bank_mask:0xf
	v_mov_b32_dpp v117, v113 row_shl:15 row_mask:0xf bank_mask:0xf
	v_mov_b32_dpp v119, v105 row_shr:2 row_mask:0xf bank_mask:0xf
	v_mov_b32_dpp v116, v104 row_shr:1 row_mask:0xf bank_mask:0xf
	v_mov_b32_dpp v117, v105 row_shr:1 row_mask:0xf bank_mask:0xf
	v_pk_fma_f32 v[112:113], v[76:77], v[118:119], v[88:89]
	v_pk_fma_f32 v[102:103], v[102:103], v[82:83], v[110:111]
	v_pk_fma_f32 v[112:113], v[80:81], v[116:117], v[112:113]
	v_pk_mul_f32 v[110:111], v[102:103], s[48:49] op_sel_hi:[1,0]
	v_pk_fma_f32 v[104:105], v[104:105], v[84:85], v[112:113]
	v_exp_f32_e32 v110, v110
	v_exp_f32_e32 v111, v111
	v_pk_mul_f32 v[112:113], v[104:105], s[48:49] op_sel_hi:[1,0]
	v_cvt_pk_bf16_f32 v125, v132, v133
	global_store_dwordx4 v[126:127], v[122:125], off
	v_exp_f32_e32 v112, v112
	v_exp_f32_e32 v113, v113
	v_pk_add_f32 v[110:111], v[110:111], 1.0 op_sel_hi:[1,0]
	v_pk_mul_f32 v[72:73], v[72:73], v[114:115]
	v_rcp_f32_e32 v110, v110
	v_rcp_f32_e32 v111, v111
	v_pk_add_f32 v[112:113], v[112:113], 1.0 op_sel_hi:[1,0]
	v_pk_mul_f32 v[102:103], v[102:103], v[110:111]
	v_rcp_f32_e32 v112, v112
	v_rcp_f32_e32 v113, v113
	v_pk_mul_f32 v[102:103], v[66:67], v[102:103]
	v_pk_mul_f32 v[66:67], v[104:105], v[112:113]
	s_nop 0
	v_pk_mul_f32 v[104:105], v[68:69], v[66:67]
	v_cvt_pk_bf16_f32 v66, v70, v71
	v_or_b32_e32 v70, 48, v168
	v_mad_i64_i32 v[70:71], s[58:59], v70, s74, v[156:157]
	v_cvt_pk_bf16_f32 v67, v72, v73
	v_cvt_pk_bf16_f32 v68, v102, v103
	v_cvt_pk_bf16_f32 v69, v104, v105
	v_lshl_add_u64 v[70:71], v[70:71], 0, v[154:155]
	global_store_dwordx4 v[70:71], v[66:69], off
	s_nop 1
	v_mov_b32_e32 v66, 0
	v_mov_b32_e32 v67, 0
	v_mov_b32_e32 v68, 0
	v_mov_b32_e32 v69, 0
	s_and_saveexec_b64 s[58:59], s[6:7]
	s_cbranch_execz .LBB0_1749
	ds_read_b128 v[162:165], v201
	ds_read_b128 v[66:69], v201 offset:16
; #define PG8_LAS __attribute__((address_space(3)))
;     __device__ __forceinline__ void operator()(const f32x4 (&acc)[2][2][4][2], const Unit& u, int wr, int wc, int fr, int fq) const {
;     ...
;         const int row0 = u.pm * BM + wr * 64 + fr;
; #pragma unroll
;         for (int ai = 0; ai < 2; ++ai) {
;             f32x4 P[2] = {{0.f, 0.f, 0.f, 0.f}, {0.f, 0.f, 0.f, 0.f}};
;             if (!(ai == 0 && wr == 0) && fr >= 14) { const int pai = (wr == 1) ? ai : ai - 1, pwr = (wr == 1) ? 0 : 1;
;                 const PG8_LAS float* p = X + ((pai * 2 + pwr) * 2 + (fr - 14)) * 128 + cl; P[0] = *(const PG8_LAS f32x4*)p; P[1] = *(const PG8_LAS f32x4*)(p + 4); }
; #pragma unroll
;             for (int m = 0; m < 4; ++m) {
;                 f32x4 r[2];
; #pragma unroll
;                 for (int n = 0; n < 2; ++n)
; #pragma unroll
;                     for (int h = 0; h < 2; ++h) {
;                         f32x2 cur, p1, p2;
; #pragma unroll
;                         for (int q = 0; q < 2; ++q) { const int i = 2 * h + q;
;                             const float c_ = acc[ai][0][m][n][i], prev = (m == 0) ? P[n][i] : acc[ai][0][m == 0 ? 0 : m - 1][n][i];
;                             cur[q] = c_; p1[q] = dpp_ctl_shr1(dpp_ctl_shl15(prev), c_); p2[q] = dpp_ctl_shr2(dpp_ctl_shl14(prev), c_); }
;                         const f32x2 kb2 = {kb[n][2 * h], kb[n][2 * h + 1]}, k02 = {k0[n][2 * h], k0[n][2 * h + 1]}, k12 = {k1[n][2 * h], k1[n][2 * h + 1]}, k22 = {k2[n][2 * h], k2[n][2 * h + 1]};
;                         const f32x2 up2 = {acc[ai][1][m][n][2 * h], acc[ai][1][m][n][2 * h + 1]};
;                         const f32x2 cv = kb2 + k02 * p2 + k12 * p1 + k22 * cur;
;                         const f32x2 ex = cv * (-1.4426950408889634f);
;                         f32x2 den; den.x = __builtin_amdgcn_exp2f(ex.x); den.y = __builtin_amdgcn_exp2f(ex.y); den = den + 1.0f;
;                         f32x2 rc; rc.x = __builtin_amdgcn_rcpf(den.x); rc.y = __builtin_amdgcn_rcpf(den.y);
;                         const f32x2 o = (cv * rc) * up2;
;                         r[n][2 * h] = o.x; r[n][2 * h + 1] = o.y;
;                     }
;                 *(u32x4*)(ACT + (size_t)(row0 + ai * HALF + m * 16) * 2816 + f0) = pack8(r[0], r[1]);
;             }
.LBB0_1749:
	s_or_b64 exec, exec, s[58:59]
	s_waitcnt lgkmcnt(1)
	v_mov_b32_dpp v72, v162 row_shl:14 row_mask:0xf bank_mask:0xf
	v_mov_b32_dpp v73, v163 row_shl:14 row_mask:0xf bank_mask:0xf
	v_mov_b32_dpp v70, v162 row_shl:15 row_mask:0xf bank_mask:0xf
	v_mov_b32_dpp v72, v54 row_shr:2 row_mask:0xf bank_mask:0xf
	v_mov_b32_dpp v71, v163 row_shl:15 row_mask:0xf bank_mask:0xf
	v_mov_b32_dpp v73, v55 row_shr:2 row_mask:0xf bank_mask:0xf
	v_mov_b32_dpp v104, v164 row_shl:14 row_mask:0xf bank_mask:0xf
	v_mov_b32_dpp v105, v165 row_shl:14 row_mask:0xf bank_mask:0xf
	v_mov_b32_dpp v70, v54 row_shr:1 row_mask:0xf bank_mask:0xf
	v_mov_b32_dpp v71, v55 row_shr:1 row_mask:0xf bank_mask:0xf
	v_pk_fma_f32 v[72:73], v[90:91], v[72:73], v[106:107]
	v_mov_b32_dpp v102, v164 row_shl:15 row_mask:0xf bank_mask:0xf
	v_mov_b32_dpp v104, v56 row_shr:2 row_mask:0xf bank_mask:0xf
	v_mov_b32_dpp v103, v165 row_shl:15 row_mask:0xf bank_mask:0xf
	v_mov_b32_dpp v105, v57 row_shr:2 row_mask:0xf bank_mask:0xf
	v_pk_fma_f32 v[70:71], v[94:95], v[70:71], v[72:73]
	v_mov_b32_dpp v102, v56 row_shr:1 row_mask:0xf bank_mask:0xf
	v_mov_b32_dpp v103, v57 row_shr:1 row_mask:0xf bank_mask:0xf
	v_pk_fma_f32 v[104:105], v[92:93], v[104:105], v[108:109]
	v_pk_fma_f32 v[70:71], v[54:55], v[98:99], v[70:71]
	v_pk_fma_f32 v[102:103], v[96:97], v[102:103], v[104:105]
	v_pk_mul_f32 v[72:73], v[70:71], s[48:49] op_sel_hi:[1,0]
	v_pk_fma_f32 v[102:103], v[56:57], v[100:101], v[102:103]
	v_exp_f32_e32 v72, v72
	v_exp_f32_e32 v73, v73
	v_pk_mul_f32 v[104:105], v[102:103], s[48:49] op_sel_hi:[1,0]
	v_add_u32_e32 v110, 0x80, v168
	v_exp_f32_e32 v104, v104
	v_exp_f32_e32 v105, v105
	v_pk_add_f32 v[72:73], v[72:73], 1.0 op_sel_hi:[1,0]
	s_andn2_b64 vcc, exec, s[8:9]
	v_rcp_f32_e32 v72, v72
	v_rcp_f32_e32 v73, v73
	v_pk_add_f32 v[104:105], v[104:105], 1.0 op_sel_hi:[1,0]
	s_mov_b64 s[8:9], -1
	v_rcp_f32_e32 v104, v104
	v_rcp_f32_e32 v105, v105
	v_pk_mul_f32 v[70:71], v[70:71], v[72:73]
	v_pk_mul_f32 v[62:63], v[62:63], v[70:71]
	v_pk_mul_f32 v[70:71], v[102:103], v[104:105]
	s_waitcnt lgkmcnt(0)
	v_mov_b32_dpp v102, v66 row_shl:14 row_mask:0xf bank_mask:0xf
	v_mov_b32_dpp v103, v67 row_shl:14 row_mask:0xf bank_mask:0xf
	s_nop 0
	v_mov_b32_dpp v102, v50 row_shr:2 row_mask:0xf bank_mask:0xf
	s_nop 0
	v_mov_b32_dpp v103, v51 row_shr:2 row_mask:0xf bank_mask:0xf
	v_mov_b32_dpp v72, v66 row_shl:15 row_mask:0xf bank_mask:0xf
	v_mov_b32_dpp v73, v67 row_shl:15 row_mask:0xf bank_mask:0xf
	v_pk_fma_f32 v[66:67], v[74:75], v[102:103], v[86:87]
	v_mov_b32_dpp v104, v68 row_shl:14 row_mask:0xf bank_mask:0xf
	v_mov_b32_dpp v105, v69 row_shl:14 row_mask:0xf bank_mask:0xf
	v_mov_b32_dpp v72, v50 row_shr:1 row_mask:0xf bank_mask:0xf
	v_mov_b32_dpp v73, v51 row_shr:1 row_mask:0xf bank_mask:0xf
	v_mov_b32_dpp v102, v68 row_shl:15 row_mask:0xf bank_mask:0xf
	v_mov_b32_dpp v104, v52 row_shr:2 row_mask:0xf bank_mask:0xf
	v_mov_b32_dpp v103, v69 row_shl:15 row_mask:0xf bank_mask:0xf
	v_mov_b32_dpp v105, v53 row_shr:2 row_mask:0xf bank_mask:0xf
	v_pk_fma_f32 v[66:67], v[78:79], v[72:73], v[66:67]
	v_mov_b32_dpp v102, v52 row_shr:1 row_mask:0xf bank_mask:0xf
	v_mov_b32_dpp v103, v53 row_shr:1 row_mask:0xf bank_mask:0xf
	v_pk_fma_f32 v[68:69], v[76:77], v[104:105], v[88:89]
	v_pk_fma_f32 v[66:67], v[50:51], v[82:83], v[66:67]
	v_pk_fma_f32 v[68:69], v[80:81], v[102:103], v[68:69]
	v_pk_mul_f32 v[72:73], v[66:67], s[48:49] op_sel_hi:[1,0]
	v_pk_fma_f32 v[68:69], v[52:53], v[84:85], v[68:69]
	v_exp_f32_e32 v72, v72
	v_exp_f32_e32 v73, v73
	v_pk_mul_f32 v[102:103], v[68:69], s[48:49] op_sel_hi:[1,0]
	v_pk_mul_f32 v[64:65], v[64:65], v[70:71]
	v_exp_f32_e32 v102, v102
	v_exp_f32_e32 v103, v103
	v_pk_add_f32 v[72:73], v[72:73], 1.0 op_sel_hi:[1,0]
	v_rcp_f32_e32 v72, v72
	v_rcp_f32_e32 v73, v73
	v_pk_add_f32 v[102:103], v[102:103], 1.0 op_sel_hi:[1,0]
	v_rcp_f32_e32 v102, v102
	v_rcp_f32_e32 v103, v103
	v_pk_mul_f32 v[66:67], v[66:67], v[72:73]
	v_mov_b32_dpp v70, v56 row_shl:14 row_mask:0xf bank_mask:0xf
	v_pk_mul_f32 v[58:59], v[58:59], v[66:67]
	v_pk_mul_f32 v[66:67], v[68:69], v[102:103]
	v_pk_mul_f32 v[66:67], v[60:61], v[66:67]
	v_mov_b32_dpp v68, v54 row_shl:14 row_mask:0xf bank_mask:0xf
	v_mov_b32_dpp v69, v55 row_shl:14 row_mask:0xf bank_mask:0xf
	v_cvt_pk_bf16_f32 v60, v62, v63
	v_cvt_pk_bf16_f32 v61, v64, v65
	v_cvt_pk_bf16_f32 v62, v58, v59
	v_cvt_pk_bf16_f32 v63, v66, v67
	v_mov_b32_dpp v68, v38 row_shr:2 row_mask:0xf bank_mask:0xf
	v_mov_b32_dpp v69, v39 row_shr:2 row_mask:0xf bank_mask:0xf
	v_mov_b32_dpp v66, v54 row_shl:15 row_mask:0xf bank_mask:0xf
	v_mov_b32_dpp v67, v55 row_shl:15 row_mask:0xf bank_mask:0xf
	v_pk_fma_f32 v[54:55], v[90:91], v[68:69], v[106:107]
	v_mov_b32_dpp v71, v57 row_shl:14 row_mask:0xf bank_mask:0xf
	v_mov_b32_dpp v66, v38 row_shr:1 row_mask:0xf bank_mask:0xf
	v_mov_b32_dpp v67, v39 row_shr:1 row_mask:0xf bank_mask:0xf
	v_mov_b32_dpp v68, v56 row_shl:15 row_mask:0xf bank_mask:0xf
	v_mov_b32_dpp v70, v40 row_shr:2 row_mask:0xf bank_mask:0xf
	v_mov_b32_dpp v69, v57 row_shl:15 row_mask:0xf bank_mask:0xf
	v_mov_b32_dpp v71, v41 row_shr:2 row_mask:0xf bank_mask:0xf
	v_pk_fma_f32 v[54:55], v[94:95], v[66:67], v[54:55]
	v_mov_b32_dpp v68, v40 row_shr:1 row_mask:0xf bank_mask:0xf
	v_mov_b32_dpp v69, v41 row_shr:1 row_mask:0xf bank_mask:0xf
	v_pk_fma_f32 v[56:57], v[92:93], v[70:71], v[108:109]
	v_pk_fma_f32 v[54:55], v[38:39], v[98:99], v[54:55]
	v_pk_fma_f32 v[56:57], v[96:97], v[68:69], v[56:57]
	v_pk_mul_f32 v[66:67], v[54:55], s[48:49] op_sel_hi:[1,0]
	v_pk_fma_f32 v[56:57], v[40:41], v[100:101], v[56:57]
	v_exp_f32_e32 v66, v66
	v_exp_f32_e32 v67, v67
; #define PG8_LAS __attribute__((address_space(3)))
;     __device__ __forceinline__ void operator()(const f32x4 (&acc)[2][2][4][2], const Unit& u, int wr, int wc, int fr, int fq) const {
;     ...
;         const int row0 = u.pm * BM + wr * 64 + fr;
; #pragma unroll
;         for (int ai = 0; ai < 2; ++ai) {
;             f32x4 P[2] = {{0.f, 0.f, 0.f, 0.f}, {0.f, 0.f, 0.f, 0.f}};
;             if (!(ai == 0 && wr == 0) && fr >= 14) { const int pai = (wr == 1) ? ai : ai - 1, pwr = (wr == 1) ? 0 : 1;
;                 const PG8_LAS float* p = X + ((pai * 2 + pwr) * 2 + (fr - 14)) * 128 + cl; P[0] = *(const PG8_LAS f32x4*)p; P[1] = *(const PG8_LAS f32x4*)(p + 4); }
; #pragma unroll
;             for (int m = 0; m < 4; ++m) {
;                 f32x4 r[2];
; #pragma unroll
;                 for (int n = 0; n < 2; ++n)
; #pragma unroll
;                     for (int h = 0; h < 2; ++h) {
;                         f32x2 cur, p1, p2;
; #pragma unroll
;                         for (int q = 0; q < 2; ++q) { const int i = 2 * h + q;
;                             const float c_ = acc[ai][0][m][n][i], prev = (m == 0) ? P[n][i] : acc[ai][0][m == 0 ? 0 : m - 1][n][i];
;                             cur[q] = c_; p1[q] = dpp_ctl_shr1(dpp_ctl_shl15(prev), c_); p2[q] = dpp_ctl_shr2(dpp_ctl_shl14(prev), c_); }
;                         const f32x2 kb2 = {kb[n][2 * h], kb[n][2 * h + 1]}, k02 = {k0[n][2 * h], k0[n][2 * h + 1]}, k12 = {k1[n][2 * h], k1[n][2 * h + 1]}, k22 = {k2[n][2 * h], k2[n][2 * h + 1]};
;                         const f32x2 up2 = {acc[ai][1][m][n][2 * h], acc[ai][1][m][n][2 * h + 1]};
;                         const f32x2 cv = kb2 + k02 * p2 + k12 * p1 + k22 * cur;
;                         const f32x2 ex = cv * (-1.4426950408889634f);
;                         f32x2 den; den.x = __builtin_amdgcn_exp2f(ex.x); den.y = __builtin_amdgcn_exp2f(ex.y); den = den + 1.0f;
;                         f32x2 rc; rc.x = __builtin_amdgcn_rcpf(den.x); rc.y = __builtin_amdgcn_rcpf(den.y);
;                         const f32x2 o = (cv * rc) * up2;
;                         r[n][2 * h] = o.x; r[n][2 * h + 1] = o.y;
;                     }
;                 *(u32x4*)(ACT + (size_t)(row0 + ai * HALF + m * 16) * 2816 + f0) = pack8(r[0], r[1]);
;             }
	v_pk_mul_f32 v[68:69], v[56:57], s[48:49] op_sel_hi:[1,0]
	v_mov_b64_e32 v[58:59], s[14:15]
	v_exp_f32_e32 v68, v68
	v_exp_f32_e32 v69, v69
	v_pk_add_f32 v[66:67], v[66:67], 1.0 op_sel_hi:[1,0]
	v_mad_i64_i32 v[64:65], s[58:59], v110, s74, v[58:59]
	v_rcp_f32_e32 v66, v66
	v_rcp_f32_e32 v67, v67
	v_pk_add_f32 v[68:69], v[68:69], 1.0 op_sel_hi:[1,0]
	v_lshl_add_u64 v[64:65], v[64:65], 0, v[154:155]
	v_rcp_f32_e32 v68, v68
	v_rcp_f32_e32 v69, v69
	global_store_dwordx4 v[64:65], v[60:63], off
	v_pk_mul_f32 v[54:55], v[54:55], v[66:67]
	s_nop 0
	v_pk_mul_f32 v[46:47], v[46:47], v[54:55]
	v_mov_b32_dpp v60, v50 row_shl:14 row_mask:0xf bank_mask:0xf
	v_mov_b32_dpp v61, v51 row_shl:14 row_mask:0xf bank_mask:0xf
	v_pk_mul_f32 v[54:55], v[56:57], v[68:69]
	v_mov_b32_dpp v60, v34 row_shr:2 row_mask:0xf bank_mask:0xf
	v_mov_b32_dpp v61, v35 row_shr:2 row_mask:0xf bank_mask:0xf
	v_mov_b32_dpp v56, v50 row_shl:15 row_mask:0xf bank_mask:0xf
	v_mov_b32_dpp v57, v51 row_shl:15 row_mask:0xf bank_mask:0xf
	v_pk_fma_f32 v[50:51], v[74:75], v[60:61], v[86:87]
	v_mov_b32_dpp v62, v52 row_shl:14 row_mask:0xf bank_mask:0xf
	v_mov_b32_dpp v63, v53 row_shl:14 row_mask:0xf bank_mask:0xf
	v_mov_b32_dpp v56, v34 row_shr:1 row_mask:0xf bank_mask:0xf
	v_mov_b32_dpp v57, v35 row_shr:1 row_mask:0xf bank_mask:0xf
	v_mov_b32_dpp v60, v52 row_shl:15 row_mask:0xf bank_mask:0xf
	v_mov_b32_dpp v62, v36 row_shr:2 row_mask:0xf bank_mask:0xf
	v_mov_b32_dpp v61, v53 row_shl:15 row_mask:0xf bank_mask:0xf
	v_mov_b32_dpp v63, v37 row_shr:2 row_mask:0xf bank_mask:0xf
	v_pk_fma_f32 v[50:51], v[78:79], v[56:57], v[50:51]
	v_mov_b32_dpp v60, v36 row_shr:1 row_mask:0xf bank_mask:0xf
	v_mov_b32_dpp v61, v37 row_shr:1 row_mask:0xf bank_mask:0xf
	v_pk_fma_f32 v[52:53], v[76:77], v[62:63], v[88:89]
	v_pk_fma_f32 v[50:51], v[34:35], v[82:83], v[50:51]
	v_pk_fma_f32 v[52:53], v[80:81], v[60:61], v[52:53]
	v_pk_mul_f32 v[56:57], v[50:51], s[48:49] op_sel_hi:[1,0]
	v_pk_fma_f32 v[52:53], v[36:37], v[84:85], v[52:53]
	v_exp_f32_e32 v56, v56
	v_exp_f32_e32 v57, v57
	v_pk_mul_f32 v[60:61], v[52:53], s[48:49] op_sel_hi:[1,0]
	v_pk_mul_f32 v[48:49], v[48:49], v[54:55]
	v_exp_f32_e32 v60, v60
	v_exp_f32_e32 v61, v61
	v_pk_add_f32 v[56:57], v[56:57], 1.0 op_sel_hi:[1,0]
	v_pk_add_f32 v[60:61], v[60:61], 1.0 op_sel_hi:[1,0]
	v_rcp_f32_e32 v56, v56
	v_rcp_f32_e32 v57, v57
	v_rcp_f32_e32 v60, v60
	v_rcp_f32_e32 v61, v61
	v_pk_mul_f32 v[50:51], v[50:51], v[56:57]
	s_nop 0
	v_pk_mul_f32 v[50:51], v[42:43], v[50:51]
	v_pk_mul_f32 v[42:43], v[52:53], v[60:61]
	s_nop 0
	v_pk_mul_f32 v[52:53], v[44:45], v[42:43]
	v_cvt_pk_bf16_f32 v42, v46, v47
	v_cvt_pk_bf16_f32 v43, v48, v49
	v_cvt_pk_bf16_f32 v44, v50, v51
	v_cvt_pk_bf16_f32 v45, v52, v53
	v_mov_b32_dpp v50, v38 row_shl:14 row_mask:0xf bank_mask:0xf
	v_mov_b32_dpp v51, v39 row_shl:14 row_mask:0xf bank_mask:0xf
	s_nop 0
	v_mov_b32_dpp v50, v22 row_shr:2 row_mask:0xf bank_mask:0xf
	s_nop 0
	v_mov_b32_dpp v51, v23 row_shr:2 row_mask:0xf bank_mask:0xf
	v_mov_b32_dpp v48, v38 row_shl:15 row_mask:0xf bank_mask:0xf
	v_mov_b32_dpp v49, v39 row_shl:15 row_mask:0xf bank_mask:0xf
	v_pk_fma_f32 v[38:39], v[90:91], v[50:51], v[106:107]
	v_mov_b32_dpp v52, v40 row_shl:14 row_mask:0xf bank_mask:0xf
	v_mov_b32_dpp v53, v41 row_shl:14 row_mask:0xf bank_mask:0xf
	v_mov_b32_dpp v48, v22 row_shr:1 row_mask:0xf bank_mask:0xf
	v_mov_b32_dpp v49, v23 row_shr:1 row_mask:0xf bank_mask:0xf
	v_mov_b32_dpp v50, v40 row_shl:15 row_mask:0xf bank_mask:0xf
	v_mov_b32_dpp v52, v24 row_shr:2 row_mask:0xf bank_mask:0xf
	v_mov_b32_dpp v51, v41 row_shl:15 row_mask:0xf bank_mask:0xf
	v_mov_b32_dpp v53, v25 row_shr:2 row_mask:0xf bank_mask:0xf
	v_pk_fma_f32 v[38:39], v[94:95], v[48:49], v[38:39]
	v_mov_b32_dpp v50, v24 row_shr:1 row_mask:0xf bank_mask:0xf
	v_mov_b32_dpp v51, v25 row_shr:1 row_mask:0xf bank_mask:0xf
	v_pk_fma_f32 v[40:41], v[92:93], v[52:53], v[108:109]
	v_pk_fma_f32 v[38:39], v[22:23], v[98:99], v[38:39]
	v_pk_fma_f32 v[40:41], v[96:97], v[50:51], v[40:41]
	v_pk_mul_f32 v[48:49], v[38:39], s[48:49] op_sel_hi:[1,0]
	v_pk_fma_f32 v[40:41], v[24:25], v[100:101], v[40:41]
	v_exp_f32_e32 v48, v48
	v_exp_f32_e32 v49, v49
	v_pk_mul_f32 v[50:51], v[40:41], s[48:49] op_sel_hi:[1,0]
	v_add_u32_e32 v46, 0x90, v168
	v_exp_f32_e32 v50, v50
	v_exp_f32_e32 v51, v51
	v_pk_add_f32 v[48:49], v[48:49], 1.0 op_sel_hi:[1,0]
	v_mad_i64_i32 v[46:47], s[58:59], v46, s74, v[58:59]
	v_rcp_f32_e32 v48, v48
	v_rcp_f32_e32 v49, v49
	v_pk_add_f32 v[50:51], v[50:51], 1.0 op_sel_hi:[1,0]
	v_lshl_add_u64 v[46:47], v[46:47], 0, v[154:155]
	v_rcp_f32_e32 v50, v50
	v_rcp_f32_e32 v51, v51
	global_store_dwordx4 v[46:47], v[42:45], off
	v_pk_mul_f32 v[38:39], v[38:39], v[48:49]
	s_nop 0
	v_pk_mul_f32 v[30:31], v[30:31], v[38:39]
	v_mov_b32_dpp v42, v34 row_shl:14 row_mask:0xf bank_mask:0xf
	v_mov_b32_dpp v43, v35 row_shl:14 row_mask:0xf bank_mask:0xf
	v_pk_mul_f32 v[38:39], v[40:41], v[50:51]
	v_mov_b32_dpp v42, v14 row_shr:2 row_mask:0xf bank_mask:0xf
	v_mov_b32_dpp v43, v15 row_shr:2 row_mask:0xf bank_mask:0xf
	v_mov_b32_dpp v40, v34 row_shl:15 row_mask:0xf bank_mask:0xf
	v_mov_b32_dpp v41, v35 row_shl:15 row_mask:0xf bank_mask:0xf
	v_pk_fma_f32 v[34:35], v[74:75], v[42:43], v[86:87]
	v_mov_b32_dpp v44, v36 row_shl:14 row_mask:0xf bank_mask:0xf
	v_mov_b32_dpp v45, v37 row_shl:14 row_mask:0xf bank_mask:0xf
	v_mov_b32_dpp v40, v14 row_shr:1 row_mask:0xf bank_mask:0xf
	v_mov_b32_dpp v41, v15 row_shr:1 row_mask:0xf bank_mask:0xf
	v_mov_b32_dpp v42, v36 row_shl:15 row_mask:0xf bank_mask:0xf
	v_mov_b32_dpp v44, v16 row_shr:2 row_mask:0xf bank_mask:0xf
	v_mov_b32_dpp v43, v37 row_shl:15 row_mask:0xf bank_mask:0xf
; #define PG8_LAS __attribute__((address_space(3)))
;     __device__ __forceinline__ void operator()(const f32x4 (&acc)[2][2][4][2], const Unit& u, int wr, int wc, int fr, int fq) const {
;     ...
;         const int row0 = u.pm * BM + wr * 64 + fr;
; #pragma unroll
;         for (int ai = 0; ai < 2; ++ai) {
;             f32x4 P[2] = {{0.f, 0.f, 0.f, 0.f}, {0.f, 0.f, 0.f, 0.f}};
;             if (!(ai == 0 && wr == 0) && fr >= 14) { const int pai = (wr == 1) ? ai : ai - 1, pwr = (wr == 1) ? 0 : 1;
;                 const PG8_LAS float* p = X + ((pai * 2 + pwr) * 2 + (fr - 14)) * 128 + cl; P[0] = *(const PG8_LAS f32x4*)p; P[1] = *(const PG8_LAS f32x4*)(p + 4); }
; #pragma unroll
;             for (int m = 0; m < 4; ++m) {
;                 f32x4 r[2];
; #pragma unroll
;                 for (int n = 0; n < 2; ++n)
; #pragma unroll
;                     for (int h = 0; h < 2; ++h) {
;                         f32x2 cur, p1, p2;
; #pragma unroll
;                         for (int q = 0; q < 2; ++q) { const int i = 2 * h + q;
;                             const float c_ = acc[ai][0][m][n][i], prev = (m == 0) ? P[n][i] : acc[ai][0][m == 0 ? 0 : m - 1][n][i];
;                             cur[q] = c_; p1[q] = dpp_ctl_shr1(dpp_ctl_shl15(prev), c_); p2[q] = dpp_ctl_shr2(dpp_ctl_shl14(prev), c_); }
;                         const f32x2 kb2 = {kb[n][2 * h], kb[n][2 * h + 1]}, k02 = {k0[n][2 * h], k0[n][2 * h + 1]}, k12 = {k1[n][2 * h], k1[n][2 * h + 1]}, k22 = {k2[n][2 * h], k2[n][2 * h + 1]};
;                         const f32x2 up2 = {acc[ai][1][m][n][2 * h], acc[ai][1][m][n][2 * h + 1]};
;                         const f32x2 cv = kb2 + k02 * p2 + k12 * p1 + k22 * cur;
;                         const f32x2 ex = cv * (-1.4426950408889634f);
;                         f32x2 den; den.x = __builtin_amdgcn_exp2f(ex.x); den.y = __builtin_amdgcn_exp2f(ex.y); den = den + 1.0f;
;                         f32x2 rc; rc.x = __builtin_amdgcn_rcpf(den.x); rc.y = __builtin_amdgcn_rcpf(den.y);
;                         const f32x2 o = (cv * rc) * up2;
;                         r[n][2 * h] = o.x; r[n][2 * h + 1] = o.y;
;                     }
;                 *(u32x4*)(ACT + (size_t)(row0 + ai * HALF + m * 16) * 2816 + f0) = pack8(r[0], r[1]);
;             }
	v_mov_b32_dpp v45, v17 row_shr:2 row_mask:0xf bank_mask:0xf
	v_pk_fma_f32 v[34:35], v[78:79], v[40:41], v[34:35]
	v_mov_b32_dpp v42, v16 row_shr:1 row_mask:0xf bank_mask:0xf
	v_mov_b32_dpp v43, v17 row_shr:1 row_mask:0xf bank_mask:0xf
	v_pk_fma_f32 v[36:37], v[76:77], v[44:45], v[88:89]
	v_pk_fma_f32 v[34:35], v[14:15], v[82:83], v[34:35]
	v_pk_fma_f32 v[36:37], v[80:81], v[42:43], v[36:37]
	v_pk_mul_f32 v[40:41], v[34:35], s[48:49] op_sel_hi:[1,0]
	v_pk_fma_f32 v[36:37], v[16:17], v[84:85], v[36:37]
	v_exp_f32_e32 v40, v40
	v_exp_f32_e32 v41, v41
	v_pk_mul_f32 v[42:43], v[36:37], s[48:49] op_sel_hi:[1,0]
	v_pk_mul_f32 v[32:33], v[32:33], v[38:39]
	v_exp_f32_e32 v42, v42
	v_exp_f32_e32 v43, v43
	v_pk_add_f32 v[40:41], v[40:41], 1.0 op_sel_hi:[1,0]
	v_pk_add_f32 v[42:43], v[42:43], 1.0 op_sel_hi:[1,0]
	v_rcp_f32_e32 v40, v40
	v_rcp_f32_e32 v41, v41
	v_rcp_f32_e32 v42, v42
	v_rcp_f32_e32 v43, v43
	v_pk_mul_f32 v[34:35], v[34:35], v[40:41]
	s_nop 0
	v_pk_mul_f32 v[34:35], v[26:27], v[34:35]
	v_pk_mul_f32 v[26:27], v[36:37], v[42:43]
	s_nop 0
	v_pk_mul_f32 v[36:37], v[28:29], v[26:27]
	v_cvt_pk_bf16_f32 v26, v30, v31
	v_add_u32_e32 v30, 0xa0, v168
	v_mad_i64_i32 v[30:31], s[58:59], v30, s74, v[58:59]
	v_cvt_pk_bf16_f32 v27, v32, v33
	v_cvt_pk_bf16_f32 v28, v34, v35
	v_cvt_pk_bf16_f32 v29, v36, v37
	v_lshl_add_u64 v[30:31], v[30:31], 0, v[154:155]
	global_store_dwordx4 v[30:31], v[26:29], off
	v_mov_b32_dpp v26, v22 row_shl:15 row_mask:0xf bank_mask:0xf
	v_mov_b32_dpp v28, v22 row_shl:14 row_mask:0xf bank_mask:0xf
	v_mov_b32_dpp v27, v23 row_shl:15 row_mask:0xf bank_mask:0xf
	v_mov_b32_dpp v29, v23 row_shl:14 row_mask:0xf bank_mask:0xf
	v_mov_b32_dpp v22, v24 row_shl:15 row_mask:0xf bank_mask:0xf
	v_mov_b32_dpp v30, v24 row_shl:14 row_mask:0xf bank_mask:0xf
	v_mov_b32_dpp v23, v25 row_shl:15 row_mask:0xf bank_mask:0xf
	v_mov_b32_dpp v31, v25 row_shl:14 row_mask:0xf bank_mask:0xf
	v_mov_b32_dpp v32, v14 row_shl:14 row_mask:0xf bank_mask:0xf
	v_mov_b32_dpp v33, v15 row_shl:14 row_mask:0xf bank_mask:0xf
	v_mov_b32_dpp v24, v14 row_shl:15 row_mask:0xf bank_mask:0xf
	v_mov_b32_dpp v32, v10 row_shr:2 row_mask:0xf bank_mask:0xf
	v_mov_b32_dpp v25, v15 row_shl:15 row_mask:0xf bank_mask:0xf
	v_mov_b32_dpp v33, v11 row_shr:2 row_mask:0xf bank_mask:0xf
	v_mov_b32_dpp v30, v20 row_shr:2 row_mask:0xf bank_mask:0xf
	v_mov_b32_dpp v31, v21 row_shr:2 row_mask:0xf bank_mask:0xf
	v_mov_b32_dpp v24, v10 row_shr:1 row_mask:0xf bank_mask:0xf
	v_mov_b32_dpp v25, v11 row_shr:1 row_mask:0xf bank_mask:0xf
	v_pk_fma_f32 v[32:33], v[74:75], v[32:33], v[86:87]
	v_mov_b32_dpp v22, v20 row_shr:1 row_mask:0xf bank_mask:0xf
	v_mov_b32_dpp v23, v21 row_shr:1 row_mask:0xf bank_mask:0xf
	v_pk_fma_f32 v[24:25], v[78:79], v[24:25], v[32:33]
	v_pk_fma_f32 v[30:31], v[92:93], v[30:31], v[108:109]
	v_pk_fma_f32 v[10:11], v[10:11], v[82:83], v[24:25]
	v_pk_fma_f32 v[22:23], v[96:97], v[22:23], v[30:31]
	v_pk_mul_f32 v[24:25], v[10:11], s[48:49] op_sel_hi:[1,0]
	v_pk_fma_f32 v[20:21], v[20:21], v[100:101], v[22:23]
	v_exp_f32_e32 v24, v24
	v_exp_f32_e32 v25, v25
	v_pk_mul_f32 v[22:23], v[20:21], s[48:49] op_sel_hi:[1,0]
	v_exp_f32_e32 v22, v22
	v_exp_f32_e32 v23, v23
	v_pk_add_f32 v[24:25], v[24:25], 1.0 op_sel_hi:[1,0]
	v_rcp_f32_e32 v24, v24
	v_rcp_f32_e32 v25, v25
	v_pk_add_f32 v[22:23], v[22:23], 1.0 op_sel_hi:[1,0]
	v_mov_b32_dpp v28, v18 row_shr:2 row_mask:0xf bank_mask:0xf
	v_rcp_f32_e32 v22, v22
	v_rcp_f32_e32 v23, v23
	v_mov_b32_dpp v29, v19 row_shr:2 row_mask:0xf bank_mask:0xf
	v_mov_b32_dpp v34, v16 row_shl:14 row_mask:0xf bank_mask:0xf
	v_pk_mul_f32 v[10:11], v[10:11], v[24:25]
	v_mov_b32_dpp v35, v17 row_shl:14 row_mask:0xf bank_mask:0xf
	v_mov_b32_dpp v26, v18 row_shr:1 row_mask:0xf bank_mask:0xf
	v_mov_b32_dpp v27, v19 row_shr:1 row_mask:0xf bank_mask:0xf
	v_mov_b32_dpp v14, v16 row_shl:15 row_mask:0xf bank_mask:0xf
	v_mov_b32_dpp v34, v12 row_shr:2 row_mask:0xf bank_mask:0xf
	v_pk_mul_f32 v[10:11], v[2:3], v[10:11]
	v_pk_mul_f32 v[2:3], v[20:21], v[22:23]
	v_pk_fma_f32 v[20:21], v[90:91], v[28:29], v[106:107]
	v_mov_b32_dpp v15, v17 row_shl:15 row_mask:0xf bank_mask:0xf
	v_mov_b32_dpp v35, v13 row_shr:2 row_mask:0xf bank_mask:0xf
	v_mov_b32_dpp v14, v12 row_shr:1 row_mask:0xf bank_mask:0xf
	v_pk_fma_f32 v[20:21], v[94:95], v[26:27], v[20:21]
	v_mov_b32_dpp v15, v13 row_shr:1 row_mask:0xf bank_mask:0xf
	v_pk_fma_f32 v[16:17], v[76:77], v[34:35], v[88:89]
	v_pk_fma_f32 v[18:19], v[18:19], v[98:99], v[20:21]
	v_pk_fma_f32 v[14:15], v[80:81], v[14:15], v[16:17]
	v_pk_mul_f32 v[20:21], v[18:19], s[48:49] op_sel_hi:[1,0]
	v_pk_fma_f32 v[12:13], v[12:13], v[84:85], v[14:15]
	v_exp_f32_e32 v20, v20
	v_exp_f32_e32 v21, v21
	v_pk_mul_f32 v[14:15], v[12:13], s[48:49] op_sel_hi:[1,0]
	v_pk_mul_f32 v[8:9], v[8:9], v[2:3]
	v_exp_f32_e32 v14, v14
	v_exp_f32_e32 v15, v15
	v_pk_add_f32 v[16:17], v[20:21], 1.0 op_sel_hi:[1,0]
	v_pk_add_f32 v[14:15], v[14:15], 1.0 op_sel_hi:[1,0]
	v_rcp_f32_e32 v16, v16
	v_rcp_f32_e32 v17, v17
	v_rcp_f32_e32 v14, v14
	v_rcp_f32_e32 v15, v15
	v_pk_mul_f32 v[2:3], v[18:19], v[16:17]
	s_nop 0
	v_pk_mul_f32 v[2:3], v[6:7], v[2:3]
	v_pk_mul_f32 v[6:7], v[12:13], v[14:15]
	v_cvt_pk_bf16_f32 v2, v2, v3
	v_cvt_pk_bf16_f32 v3, v8, v9
	s_nop 0
	v_pk_mul_f32 v[6:7], v[4:5], v[6:7]
	v_cvt_pk_bf16_f32 v4, v10, v11
	s_nop 0
	v_cvt_pk_bf16_f32 v5, v6, v7
	v_add_u32_e32 v6, 0xb0, v168
	v_mad_i64_i32 v[6:7], s[58:59], v6, s74, v[58:59]
	v_lshl_add_u64 v[6:7], v[6:7], 0, v[154:155]
	global_store_dwordx4 v[6:7], v[2:5], off
	s_cbranch_vccnz .LBB0_1733
	s_and_b64 vcc, exec, s[10:11]
	s_cbranch_vccnz .LBB0_1732
	s_barrier
	s_branch .LBB0_1732
